# single-hop grid barrier on all 11 sites (global-last bumps all XCD generation words; static generation; cached base ptr) + GEMM K-loop heads pinned at 64B+44
# speedup vs baseline: 1.0391x; 1.0075x over previous
; #define LAS __attribute__((address_space(3)))
; __device__ __forceinline__ KP kargs() { KP k = (KP)__builtin_amdgcn_kernarg_segment_ptr(); asm volatile("" : "+s"(k)); return k; }
; __device__ __forceinline__ int tid_() { int t = threadIdx.x; asm volatile("" : "+v"(t)); return t; }
; __device__ __forceinline__ int bid_() { int t = blockIdx.x; asm volatile("" : "+s"(t)); return t; }
; __device__ __forceinline__ unsigned xb_add(unsigned* p, unsigned v) { return __hip_atomic_fetch_add(p, v, __ATOMIC_RELAXED, __HIP_MEMORY_SCOPE_AGENT); }
; __device__ __forceinline__ unsigned xb_xcc_id() { return (unsigned)__builtin_amdgcn_s_getreg((3 << 11) | 20) & 0xFu; }
; __global__ void __launch_bounds__(512, 2) fwd_megakernel(Params pv) {
;     extern __shared__ __attribute__((aligned(16))) unsigned char shm[];
;     LAS unsigned char* lds = (LAS unsigned char*)shm;
;     cg::grid_group grid = cg::this_grid();
;     if (tid_() < 4) ((LAS unsigned*)(lds + LDS_BAR_OFF))[tid_()] = 0u;
;     __syncthreads();
;     if (bid_() == 0) { unsigned* bw = (unsigned*)(kargs()->ws + WS_BAR); for (int i = tid_(); i < 4096; i += 512) __hip_atomic_store(bw + i, 0u, __ATOMIC_RELAXED, __HIP_MEMORY_SCOPE_AGENT); }
;     grid.sync();
;     if (tid_() == 0) (void)xb_add(&((unsigned*)(kargs()->ws + WS_BAR))[XB_XCNT(xb_xcc_id())], 1u);
.LBB0_20:
	s_or_b64 exec, exec, s[4:5]
	s_add_i32 s52, 0, 0x20000
	v_writelane_b32 v255, s2, 0
	v_writelane_b32 v255, s0, 1
	v_mbcnt_lo_u32_b32 v0, -1, 0
	s_add_i32 s50, 0, 0x20004
	v_writelane_b32 v255, s1, 2
	v_writelane_b32 v255, s52, 3
	s_load_dwordx2 s[4:5], s[0:1], 0xe8
	s_waitcnt lgkmcnt(0)
	s_add_u32 s4, s4, 0x1a3a8000
	s_addc_u32 s5, s5, 0
	v_writelane_b32 v255, s4, 8
	v_writelane_b32 v255, s5, 9
	s_movk_i32 s38, 0x1000
	s_movk_i32 s88, 0x7000
	s_mov_b32 s89, 0xe000
	s_mov_b32 s91, 0x15000
	s_mov_b32 s92, 0x1c000
	s_mov_b32 s93, 0x23000
	s_mov_b32 s45, 0x2a000
	s_mov_b32 s46, 0x31000
	s_mov_b32 s81, 0x38000
	s_mov_b32 s82, 0x3f000
	s_mov_b32 s49, 0x46000
	s_mov_b32 s48, 0x4d000
	s_mov_b32 s43, 0x54000
	s_mov_b32 s87, 0x5b000
	s_mov_b32 s90, 0x62000
	s_mov_b32 s94, 0x69000
	s_mov_b32 s95, 0x70000
	s_mov_b32 s20, 0x77000
	s_mov_b32 s42, 0x7e000
	s_mov_b32 s40, 0x85000
	s_mov_b32 s96, 0x8c000
	v_mov_b32_e32 v1, 0
	v_mov_b32_e32 v254, 0x3ecc95a3
	v_mov_b32_e32 v213, 0x358637bd
	v_mov_b32_e32 v215, 0x1000
	v_mov_b32_e32 v216, 0x2000
	v_mov_b32_e32 v217, 0x1a3ab000
	v_mov_b32_e32 v218, 1
	v_mov_b32_e32 v219, 0x260
	v_mov_b32_e32 v220, 0x7f800000
	v_mov_b32_e32 v204, 0x3f317218
	v_mbcnt_hi_u32_b32 v207, -1, v0
	v_mov_b32_e32 v221, 0x2c00
	v_mov_b32_e32 v222, 0x1600
	s_movk_i32 s33, 0x2800
	s_movk_i32 s41, 0x80d
	s_movk_i32 s22, 0x1600
	s_mov_b32 s47, 0xf800000
	s_mov_b32 s80, 0x40000
	s_mov_b32 s76, 0x48000
	s_mov_b32 s77, 0x50000
	s_movk_i32 s39, 0x2c00
	s_mov_b64 s[78:79], 0x40000
	s_mov_b64 s[26:27], 0x80
	s_mov_b64 s[28:29], 0x1000
	s_mov_b64 s[30:31], 0x2000
	s_mov_b64 s[36:37], 0x4120000
	s_mov_b32 s56, s17
	v_writelane_b32 v255, s50, 4
	s_branch .LBB0_23

; #define LAS __attribute__((address_space(3)))
; __device__ __forceinline__ KP kargs() { KP k = (KP)__builtin_amdgcn_kernarg_segment_ptr(); asm volatile("" : "+s"(k)); return k; }
; __device__ __forceinline__ int tid_() { int t = threadIdx.x; asm volatile("" : "+v"(t)); return t; }
; __device__ __forceinline__ unsigned xb_ld(unsigned* p)              { return __hip_atomic_load(p, __ATOMIC_RELAXED, __HIP_MEMORY_SCOPE_AGENT); }
; __device__ __forceinline__ unsigned xb_add(unsigned* p, unsigned v) { return __hip_atomic_fetch_add(p, v, __ATOMIC_RELAXED, __HIP_MEMORY_SCOPE_AGENT); }
; __device__ __forceinline__ unsigned xb_xcc_id() { return (unsigned)__builtin_amdgcn_s_getreg((3 << 11) | 20) & 0xFu; }
; __device__ __forceinline__ void grid_barrier(LAS unsigned char* lds) {
;     asm volatile("s_waitcnt vmcnt(0)" ::: "memory");
;     __syncthreads();
;     if (tid_() == 0) {
;         unsigned* bar = (unsigned*)(kargs()->ws + WS_BAR);
;         volatile LAS unsigned* st = (volatile LAS unsigned*)(lds + LDS_BAR_OFF);
;         const unsigned x = xb_xcc_id();
;         __builtin_amdgcn_s_waitcnt(0);
;         unsigned nloc = st[0], nx = st[1];
;         if (nloc == 0u) { xcd_barrier_complete(bar, x, nloc, nx); st[0] = nloc; st[1] = nx; }
;         const unsigned old = xb_add(&bar[XB_XSUB(x)], 1u);
;         const unsigned gen = old / nloc;
;         if (old + 1u == (gen + 1u) * nloc) {
;             __builtin_amdgcn_fence(__ATOMIC_RELEASE, "agent");
;             asm volatile("s_waitcnt vmcnt(0)" ::: "memory");
;             const unsigned og = xb_add(&bar[XB_TOP], 1u);
;             const unsigned tg = og / nx;
;             if (og + 1u == (tg + 1u) * nx) xb_add(&bar[XB_TOPGEN], 1u);
;             else XB_SPIN(xb_ld(&bar[XB_TOPGEN]) == tg, bar);
;             __builtin_amdgcn_fence(__ATOMIC_ACQUIRE, "agent");
;             xb_add(&bar[XB_XGEN(x)], 1u);
;             asm volatile("s_waitcnt vmcnt(0)" ::: "memory");
;         } else {
;             XB_SPIN(xb_ld(&bar[XB_XGEN(x)]) == gen, bar);
;             __builtin_amdgcn_fence(__ATOMIC_ACQUIRE, "agent");
;             asm volatile("s_waitcnt vmcnt(0)" ::: "memory");
;         }
;     }
;     __syncthreads();
.LBB0_88:
	s_waitcnt vmcnt(0)
	v_mov_b32_e32 v0, v209
	s_barrier
	s_nop 0
	v_cmp_eq_u32_e32 vcc, 0, v0
	s_and_saveexec_b64 s[4:5], vcc
	s_cbranch_execz .LBB0_140
	s_cmp_eq_u32 s56, 0
	s_cbranch_scc1 .Lfb1_orig
	v_readlane_b32 s12, v255, 8
	v_readlane_b32 s13, v255, 9
	v_mov_b32_e32 v18, 0x20000
	ds_read2_b32 v[20:21], v18 offset1:1
	s_getreg_b32 s14, hwreg(HW_REG_XCC_ID, 0, 4)
	s_and_b32 s14, s14, 15
	s_mul_i32 s32, s56, 11
	s_add_i32 s32, s32, 0
	s_add_i32 s34, s32, 1
	v_mov_b32_e32 v19, 1
	v_mov_b32_e32 v22, 0
	s_waitcnt lgkmcnt(0)
	v_readfirstlane_b32 s24, v20
	v_readfirstlane_b32 s25, v21
	s_lshl_b32 s35, s14, 8
	s_add_u32 s70, s12, s35
	s_addc_u32 s71, s13, 0
	s_add_u32 s72, s70, 0x2400
	s_addc_u32 s73, s71, 0
	s_add_u32 s70, s70, 0x1400
	s_addc_u32 s71, s71, 0
	global_atomic_add v23, v22, v19, s[70:71] sc0
	s_mul_i32 s57, s34, s24
	s_waitcnt vmcnt(0)
	v_readfirstlane_b32 s44, v23
	s_nop 3
	s_add_i32 s44, s44, 1
	s_cmp_lg_u32 s44, s57
	s_cbranch_scc1 .Lfb1_spin
	buffer_wbl2 sc1
	s_waitcnt vmcnt(0)
	s_add_u32 s98, s12, 0x3400
	s_addc_u32 s99, s13, 0
	global_atomic_add v23, v22, v19, s[98:99] sc0
	s_mul_i32 s57, s34, s25
	s_waitcnt vmcnt(0)
	v_readfirstlane_b32 s44, v23
	s_nop 3
	s_add_i32 s44, s44, 1
	s_cmp_lg_u32 s44, s57
	s_cbranch_scc1 .Lfb1_spin
	global_atomic_add v22, v19, s[98:99] offset:256
	s_add_u32 s98, s12, 0x2400
	s_addc_u32 s99, s13, 0
	global_atomic_add v22, v19, s[98:99]
	global_atomic_add v22, v19, s[98:99] offset:256
	global_atomic_add v22, v19, s[98:99] offset:512
	global_atomic_add v22, v19, s[98:99] offset:768
	global_atomic_add v22, v19, s[98:99] offset:1024
	global_atomic_add v22, v19, s[98:99] offset:1280
	global_atomic_add v22, v19, s[98:99] offset:1536
	global_atomic_add v22, v19, s[98:99] offset:1792
	global_atomic_add v22, v19, s[98:99] offset:2048
	global_atomic_add v22, v19, s[98:99] offset:2304
	global_atomic_add v22, v19, s[98:99] offset:2560
	global_atomic_add v22, v19, s[98:99] offset:2816
	global_atomic_add v22, v19, s[98:99] offset:3072
	global_atomic_add v22, v19, s[98:99] offset:3328
	global_atomic_add v22, v19, s[98:99] offset:3584
	global_atomic_add v22, v19, s[98:99] offset:3840
.Lfb1_spin:
	s_mov_b32 s83, 0
.Lfb1_loop:
	global_load_dword v23, v22, s[72:73] sc1
	s_waitcnt vmcnt(0)
	v_readfirstlane_b32 s44, v23
	s_nop 3
	s_cmp_lg_u32 s44, s32
	s_cbranch_scc1 .Lfb1_done
	s_sleep 1
	s_add_i32 s83, s83, 1
	s_cmp_lt_u32 s83, 0x100000
	s_cbranch_scc1 .Lfb1_loop
.Lfb1_done:
	buffer_inv sc1
	s_waitcnt vmcnt(0)
	s_branch .LBB0_140
.Lfb1_orig:
	s_mov_b64 s[6:7], s[0:1]
	v_mov_b32_e32 v0, s52
	s_load_dwordx2 s[6:7], s[6:7], 0xe8
	s_getreg_b32 s8, hwreg(HW_REG_XCC_ID, 0, 4)
	s_waitcnt vmcnt(0) expcnt(0) lgkmcnt(0)
	ds_read_b32 v3, v0
	v_mov_b32_e32 v0, s50
	ds_read_b32 v0, v0
	s_and_b32 s16, s8, 15
	s_waitcnt lgkmcnt(1)
	v_cmp_ne_u32_e32 vcc, 0, v3
	s_cbranch_vccnz .LBB0_104
	s_add_u32 s8, s6, 0x1a3a8200
	s_addc_u32 s9, s7, 0
	s_add_u32 s10, s6, 0x1a3a8400
	s_addc_u32 s11, s7, 0
	s_add_u32 s12, s6, 0x1a3a8500
	s_addc_u32 s13, s7, 0
	s_add_u32 s14, s6, 0x1a3a8600
	s_addc_u32 s15, s7, 0
	s_add_u32 s58, s6, 0x1a3a8700
	s_addc_u32 s59, s7, 0
	s_add_u32 s60, s6, 0x1a3a8800
	s_addc_u32 s61, s7, 0
	s_add_u32 s62, s6, 0x1a3a8900
	s_addc_u32 s63, s7, 0
	s_add_u32 s64, s6, 0x1a3a8a00
	s_addc_u32 s65, s7, 0
	s_add_u32 s66, s6, 0x1a3a8b00
	s_addc_u32 s67, s7, 0
	s_add_u32 s68, s6, 0x1a3a8c00
	s_addc_u32 s69, s7, 0
	s_add_u32 s70, s6, 0x1a3a8d00
	s_addc_u32 s71, s7, 0
	s_add_u32 s72, s6, 0x1a3a8e00
	s_addc_u32 s73, s7, 0
	s_add_u32 s74, s6, 0x1a3a8f00
	s_addc_u32 s75, s7, 0
	s_add_u32 s76, s6, 0x1a3a9000
	s_addc_u32 s77, s7, 0
	s_add_u32 s78, s6, 0x1a3a9100
	s_addc_u32 s79, s7, 0
	s_add_u32 s80, s6, 0x1a3a9200
	s_addc_u32 s81, s7, 0
	s_add_u32 s82, s6, 0x1a3a9300
	s_addc_u32 s83, s7, 0
	s_mov_b32 s18, 1
	s_branch .LBB0_92

; template <class Epi, bool ALIGN_EPI = true, bool SP2 = true>
; __device__ __forceinline__ void gemm_phase(LAS unsigned char* lds, const Gemm g, const Order& S, const Epi& E) {
;     ...
;         const bool has_next = S.next(ui + 1, nxt);
;         const char* nA = has_next ? (const char*)(nxt.z ? g.A1 : g.A0) + (size_t)nxt.pm * tstepA + (size_t)nxt.kt0 * kstep : cA; const char* nB = has_next ? (const char*)(nxt.z ? g.B1 : g.B0) + (size_t)nxt.pn * tstepB + (size_t)nxt.kt0 * kstep : cB;
;         const int nt = cur.nkt;
;         for (int t = 0; t < nt; t += 2) {
;             const bool last = (t == nt - 2);
;             const char* a1 = cA + (size_t)(t + 1) * kstep;
;             const char* a2 = last ? nA : cA + (size_t)(t + 2) * kstep; const char* b2 = last ? nB : cB + (size_t)(t + 2) * kstep;
;             const char* a3 = a2 + kstep; const char* b3 = b2 + kstep;
;     ...
;         for (int a = 0; a < 2; ++a)
; #pragma unroll
;             for (int b = 0; b < 2; ++b)
; #pragma unroll
;                 for (int m = 0; m < 4; ++m)
; #pragma unroll
;                     for (int n = 0; n < 2; ++n) acc[a][b][m][n] = (f32x4){0.f, 0.f, 0.f, 0.f};
.LBB0_160:
	s_ashr_i32 s89, s88, 31
	s_lshl_b64 s[50:51], s[88:89], 19
	s_add_u32 s52, s23, s50
	s_addc_u32 s53, s24, s51
	s_and_b64 s[50:51], s[92:93], exec
	s_cselect_b32 s91, s53, s13
	s_cselect_b32 s90, s52, s12
	s_ashr_i32 s87, s86, 31
	s_lshl_b64 s[50:51], s[86:87], 19
	s_add_u32 s52, s60, s50
	s_addc_u32 s53, s61, s51
	s_and_b64 s[50:51], s[92:93], exec
	s_cselect_b32 s93, s53, s15
	s_cselect_b32 s92, s52, s14
	s_add_u32 s12, s12, 0x40080
	s_addc_u32 s13, s13, 0
	s_add_u32 s50, s14, 0x100
	v_mov_b32_e32 v2, 0
	s_addc_u32 s51, s15, 0
	s_mov_b32 s52, -2
	v_mov_b32_e32 v3, v2
	v_mov_b32_e32 v4, v2
	v_mov_b32_e32 v5, v2
	v_mov_b32_e32 v6, v2
	v_mov_b32_e32 v7, v2
	v_mov_b32_e32 v8, v2
	v_mov_b32_e32 v9, v2
	v_mov_b32_e32 v14, v2
	v_mov_b32_e32 v15, v2
	v_mov_b32_e32 v16, v2
	v_mov_b32_e32 v17, v2
	v_mov_b32_e32 v22, v2
	v_mov_b32_e32 v23, v2
	v_mov_b32_e32 v24, v2
	v_mov_b32_e32 v25, v2
	v_mov_b32_e32 v30, v2
	v_mov_b32_e32 v31, v2
	v_mov_b32_e32 v32, v2
	v_mov_b32_e32 v33, v2
	v_mov_b32_e32 v38, v2
	v_mov_b32_e32 v39, v2
	v_mov_b32_e32 v40, v2
	v_mov_b32_e32 v41, v2
	v_mov_b32_e32 v46, v2
	v_mov_b32_e32 v47, v2
	v_mov_b32_e32 v48, v2
	v_mov_b32_e32 v49, v2
	v_mov_b32_e32 v54, v2
	v_mov_b32_e32 v55, v2
	v_mov_b32_e32 v56, v2
	v_mov_b32_e32 v57, v2
	v_mov_b32_e32 v10, v2
	v_mov_b32_e32 v11, v2
	v_mov_b32_e32 v12, v2
	v_mov_b32_e32 v13, v2
	v_mov_b32_e32 v18, v2
	v_mov_b32_e32 v19, v2
	v_mov_b32_e32 v20, v2
	v_mov_b32_e32 v21, v2
	v_mov_b32_e32 v26, v2
	v_mov_b32_e32 v27, v2
	v_mov_b32_e32 v28, v2
	v_mov_b32_e32 v29, v2
	v_mov_b32_e32 v34, v2
	v_mov_b32_e32 v35, v2
	v_mov_b32_e32 v36, v2
	v_mov_b32_e32 v37, v2
	v_mov_b32_e32 v42, v2
	v_mov_b32_e32 v43, v2
	v_mov_b32_e32 v44, v2
	v_mov_b32_e32 v45, v2
	v_mov_b32_e32 v50, v2
	v_mov_b32_e32 v51, v2
	v_mov_b32_e32 v52, v2
	v_mov_b32_e32 v53, v2
	v_mov_b32_e32 v58, v2
	v_mov_b32_e32 v59, v2
	v_mov_b32_e32 v60, v2
	v_mov_b32_e32 v61, v2
	v_mov_b32_e32 v62, v2
	v_mov_b32_e32 v63, v2
	v_mov_b32_e32 v64, v2
	v_mov_b32_e32 v65, v2
	v_mov_b32_e32 v66, v2
	v_mov_b32_e32 v67, v2
	v_mov_b32_e32 v68, v2
	v_mov_b32_e32 v69, v2
	v_mov_b32_e32 v70, v2
	v_mov_b32_e32 v71, v2
	v_mov_b32_e32 v72, v2
	v_mov_b32_e32 v73, v2
	v_mov_b32_e32 v82, v2
	v_mov_b32_e32 v83, v2
	v_mov_b32_e32 v84, v2
	v_mov_b32_e32 v85, v2
	v_mov_b32_e32 v86, v2
	v_mov_b32_e32 v87, v2
	v_mov_b32_e32 v88, v2
	v_mov_b32_e32 v89, v2
	v_mov_b32_e32 v98, v2
	v_mov_b32_e32 v99, v2
	v_mov_b32_e32 v100, v2
	v_mov_b32_e32 v101, v2
	v_mov_b32_e32 v102, v2
	v_mov_b32_e32 v103, v2
	v_mov_b32_e32 v104, v2
	v_mov_b32_e32 v105, v2
	v_mov_b32_e32 v114, v2
	v_mov_b32_e32 v115, v2
	v_mov_b32_e32 v116, v2
	v_mov_b32_e32 v117, v2
	v_mov_b32_e32 v118, v2
	v_mov_b32_e32 v119, v2
	v_mov_b32_e32 v120, v2
	v_mov_b32_e32 v121, v2
	v_mov_b32_e32 v74, v2
	v_mov_b32_e32 v75, v2
	v_mov_b32_e32 v76, v2
	v_mov_b32_e32 v77, v2
	v_mov_b32_e32 v78, v2
	v_mov_b32_e32 v79, v2
	v_mov_b32_e32 v80, v2
	v_mov_b32_e32 v81, v2
	v_mov_b32_e32 v90, v2
	v_mov_b32_e32 v91, v2
	v_mov_b32_e32 v92, v2
	v_mov_b32_e32 v93, v2
	v_mov_b32_e32 v94, v2
	v_mov_b32_e32 v95, v2
	v_mov_b32_e32 v96, v2
	v_mov_b32_e32 v97, v2
	v_mov_b32_e32 v106, v2
	v_mov_b32_e32 v107, v2
	v_mov_b32_e32 v108, v2
	v_mov_b32_e32 v109, v2
	v_mov_b32_e32 v110, v2
	v_mov_b32_e32 v111, v2
	v_mov_b32_e32 v112, v2
	v_mov_b32_e32 v113, v2
	v_mov_b32_e32 v122, v2
	v_mov_b32_e32 v123, v2
	v_mov_b32_e32 v124, v2
	v_mov_b32_e32 v125, v2
	v_mov_b32_e32 v126, v2
	v_mov_b32_e32 v127, v2
	v_mov_b32_e32 v128, v2
	v_mov_b32_e32 v129, v2
	.p2align	6
	s_nop 0
	s_nop 0
	s_nop 0
	s_nop 0
	s_nop 0
	s_nop 0
	s_nop 0
	s_nop 0
	s_nop 0
	s_nop 0
	s_nop 0

; #define LAS __attribute__((address_space(3)))
; __device__ __forceinline__ KP kargs() { KP k = (KP)__builtin_amdgcn_kernarg_segment_ptr(); asm volatile("" : "+s"(k)); return k; }
; __device__ __forceinline__ int tid_() { int t = threadIdx.x; asm volatile("" : "+v"(t)); return t; }
; __device__ __forceinline__ unsigned xb_ld(unsigned* p)              { return __hip_atomic_load(p, __ATOMIC_RELAXED, __HIP_MEMORY_SCOPE_AGENT); }
; __device__ __forceinline__ unsigned xb_add(unsigned* p, unsigned v) { return __hip_atomic_fetch_add(p, v, __ATOMIC_RELAXED, __HIP_MEMORY_SCOPE_AGENT); }
; __device__ __forceinline__ unsigned xb_xcc_id() { return (unsigned)__builtin_amdgcn_s_getreg((3 << 11) | 20) & 0xFu; }
; __device__ __forceinline__ void grid_barrier(LAS unsigned char* lds) {
;     asm volatile("s_waitcnt vmcnt(0)" ::: "memory");
;     __syncthreads();
;     if (tid_() == 0) {
;         unsigned* bar = (unsigned*)(kargs()->ws + WS_BAR);
;         volatile LAS unsigned* st = (volatile LAS unsigned*)(lds + LDS_BAR_OFF);
;         const unsigned x = xb_xcc_id();
;         __builtin_amdgcn_s_waitcnt(0);
;         unsigned nloc = st[0], nx = st[1];
;         if (nloc == 0u) { xcd_barrier_complete(bar, x, nloc, nx); st[0] = nloc; st[1] = nx; }
;         const unsigned old = xb_add(&bar[XB_XSUB(x)], 1u);
;         const unsigned gen = old / nloc;
;         if (old + 1u == (gen + 1u) * nloc) {
;             __builtin_amdgcn_fence(__ATOMIC_RELEASE, "agent");
;             asm volatile("s_waitcnt vmcnt(0)" ::: "memory");
;             const unsigned og = xb_add(&bar[XB_TOP], 1u);
;             const unsigned tg = og / nx;
;             if (og + 1u == (tg + 1u) * nx) xb_add(&bar[XB_TOPGEN], 1u);
;             else XB_SPIN(xb_ld(&bar[XB_TOPGEN]) == tg, bar);
;             __builtin_amdgcn_fence(__ATOMIC_ACQUIRE, "agent");
;             xb_add(&bar[XB_XGEN(x)], 1u);
;             asm volatile("s_waitcnt vmcnt(0)" ::: "memory");
;         } else {
;             XB_SPIN(xb_ld(&bar[XB_XGEN(x)]) == gen, bar);
;             __builtin_amdgcn_fence(__ATOMIC_ACQUIRE, "agent");
;             asm volatile("s_waitcnt vmcnt(0)" ::: "memory");
;         }
;     }
;     __syncthreads();
.LBB0_264:
	s_waitcnt vmcnt(0)
	v_mov_b32_e32 v0, v209
	s_waitcnt vmcnt(0)
	s_barrier
	s_nop 0
	v_cmp_eq_u32_e32 vcc, 0, v0
	s_and_saveexec_b64 s[4:5], vcc
	s_movk_i32 s0, 0x400
	s_mov_b32 s1, 0xfe03f81
	s_mov_b32 s20, 0x800000
	v_readlane_b32 s52, v255, 3
	v_readlane_b32 s50, v255, 4
	s_movk_i32 s23, 0x3000
	s_movk_i32 s43, 0x2000
	s_movk_i32 s21, 0x810
	s_cbranch_execz .LBB0_316
	v_readlane_b32 s12, v255, 8
	v_readlane_b32 s13, v255, 9
	v_mov_b32_e32 v18, 0x20000
	ds_read2_b32 v[20:21], v18 offset1:1
	s_getreg_b32 s14, hwreg(HW_REG_XCC_ID, 0, 4)
	s_and_b32 s14, s14, 15
	s_mul_i32 s32, s56, 11
	s_add_i32 s32, s32, 1
	s_add_i32 s34, s32, 1
	v_mov_b32_e32 v19, 1
	v_mov_b32_e32 v22, 0
	s_waitcnt lgkmcnt(0)
	v_readfirstlane_b32 s24, v20
	v_readfirstlane_b32 s25, v21
	s_lshl_b32 s35, s14, 8
	s_add_u32 s70, s12, s35
	s_addc_u32 s71, s13, 0
	s_add_u32 s72, s70, 0x2400
	s_addc_u32 s73, s71, 0
	s_add_u32 s70, s70, 0x1400
	s_addc_u32 s71, s71, 0
	global_atomic_add v23, v22, v19, s[70:71] sc0
	s_mul_i32 s57, s34, s24
	s_waitcnt vmcnt(0)
	v_readfirstlane_b32 s44, v23
	s_nop 3
	s_add_i32 s44, s44, 1
	s_cmp_lg_u32 s44, s57
	s_cbranch_scc1 .Lfb2_spin
	buffer_wbl2 sc1
	s_waitcnt vmcnt(0)
	s_add_u32 s98, s12, 0x3400
	s_addc_u32 s99, s13, 0
	global_atomic_add v23, v22, v19, s[98:99] sc0
	s_mul_i32 s57, s34, s25
	s_waitcnt vmcnt(0)
	v_readfirstlane_b32 s44, v23
	s_nop 3
	s_add_i32 s44, s44, 1
	s_cmp_lg_u32 s44, s57
	s_cbranch_scc1 .Lfb2_spin
	global_atomic_add v22, v19, s[98:99] offset:256
	s_add_u32 s98, s12, 0x2400
	s_addc_u32 s99, s13, 0
	global_atomic_add v22, v19, s[98:99]
	global_atomic_add v22, v19, s[98:99] offset:256
	global_atomic_add v22, v19, s[98:99] offset:512
	global_atomic_add v22, v19, s[98:99] offset:768
	global_atomic_add v22, v19, s[98:99] offset:1024
	global_atomic_add v22, v19, s[98:99] offset:1280
	global_atomic_add v22, v19, s[98:99] offset:1536
	global_atomic_add v22, v19, s[98:99] offset:1792
	global_atomic_add v22, v19, s[98:99] offset:2048
	global_atomic_add v22, v19, s[98:99] offset:2304
	global_atomic_add v22, v19, s[98:99] offset:2560
	global_atomic_add v22, v19, s[98:99] offset:2816
	global_atomic_add v22, v19, s[98:99] offset:3072
	global_atomic_add v22, v19, s[98:99] offset:3328
	global_atomic_add v22, v19, s[98:99] offset:3584
	global_atomic_add v22, v19, s[98:99] offset:3840

; __device__ __forceinline__ unsigned xb_ld(unsigned* p)              { return __hip_atomic_load(p, __ATOMIC_RELAXED, __HIP_MEMORY_SCOPE_AGENT); }
; __device__ __forceinline__ unsigned xb_add(unsigned* p, unsigned v) { return __hip_atomic_fetch_add(p, v, __ATOMIC_RELAXED, __HIP_MEMORY_SCOPE_AGENT); }
; #define XB_SPIN(cond, bar) do { unsigned _sp = 0; while (cond) { __builtin_amdgcn_s_sleep(1); \
;     if ((++_sp & 255u) == 0u) { if (xb_ld(&(bar)[XB_TMO])) break; if (_sp > XB_SPIN_CAP) { atomicAdd(&(bar)[XB_TMO], 1u); break; } } } } while (0)
; __device__ __forceinline__ void grid_barrier(LAS unsigned char* lds) {
;     ...
;         const unsigned old = xb_add(&bar[XB_XSUB(x)], 1u);
;         const unsigned gen = old / nloc;
;         if (old + 1u == (gen + 1u) * nloc) {
;             __builtin_amdgcn_fence(__ATOMIC_RELEASE, "agent");
;             asm volatile("s_waitcnt vmcnt(0)" ::: "memory");
;             const unsigned og = xb_add(&bar[XB_TOP], 1u);
;             const unsigned tg = og / nx;
;             if (og + 1u == (tg + 1u) * nx) xb_add(&bar[XB_TOPGEN], 1u);
;             else XB_SPIN(xb_ld(&bar[XB_TOPGEN]) == tg, bar);
;             __builtin_amdgcn_fence(__ATOMIC_ACQUIRE, "agent");
;             xb_add(&bar[XB_XGEN(x)], 1u);
;             asm volatile("s_waitcnt vmcnt(0)" ::: "memory");
;         } else {
;             XB_SPIN(xb_ld(&bar[XB_XGEN(x)]) == gen, bar);
;             __builtin_amdgcn_fence(__ATOMIC_ACQUIRE, "agent");
;             asm volatile("s_waitcnt vmcnt(0)" ::: "memory");
;         }
.Lfb2_done:
	buffer_inv sc1
	s_waitcnt vmcnt(0)

; #define LAS __attribute__((address_space(3)))
; __device__ __forceinline__ KP kargs() { KP k = (KP)__builtin_amdgcn_kernarg_segment_ptr(); asm volatile("" : "+s"(k)); return k; }
; __device__ __forceinline__ int tid_() { int t = threadIdx.x; asm volatile("" : "+v"(t)); return t; }
; __device__ __forceinline__ unsigned xb_ld(unsigned* p)              { return __hip_atomic_load(p, __ATOMIC_RELAXED, __HIP_MEMORY_SCOPE_AGENT); }
; __device__ __forceinline__ unsigned xb_add(unsigned* p, unsigned v) { return __hip_atomic_fetch_add(p, v, __ATOMIC_RELAXED, __HIP_MEMORY_SCOPE_AGENT); }
; __device__ __forceinline__ unsigned xb_xcc_id() { return (unsigned)__builtin_amdgcn_s_getreg((3 << 11) | 20) & 0xFu; }
; __device__ __forceinline__ void grid_barrier(LAS unsigned char* lds) {
;     asm volatile("s_waitcnt vmcnt(0)" ::: "memory");
;     __syncthreads();
;     if (tid_() == 0) {
;         unsigned* bar = (unsigned*)(kargs()->ws + WS_BAR);
;         volatile LAS unsigned* st = (volatile LAS unsigned*)(lds + LDS_BAR_OFF);
;         const unsigned x = xb_xcc_id();
;         __builtin_amdgcn_s_waitcnt(0);
;         unsigned nloc = st[0], nx = st[1];
;         if (nloc == 0u) { xcd_barrier_complete(bar, x, nloc, nx); st[0] = nloc; st[1] = nx; }
;         const unsigned old = xb_add(&bar[XB_XSUB(x)], 1u);
;         const unsigned gen = old / nloc;
;         if (old + 1u == (gen + 1u) * nloc) {
;             __builtin_amdgcn_fence(__ATOMIC_RELEASE, "agent");
;             asm volatile("s_waitcnt vmcnt(0)" ::: "memory");
;             const unsigned og = xb_add(&bar[XB_TOP], 1u);
;             const unsigned tg = og / nx;
;             if (og + 1u == (tg + 1u) * nx) xb_add(&bar[XB_TOPGEN], 1u);
;             else XB_SPIN(xb_ld(&bar[XB_TOPGEN]) == tg, bar);
;             __builtin_amdgcn_fence(__ATOMIC_ACQUIRE, "agent");
;             xb_add(&bar[XB_XGEN(x)], 1u);
;             asm volatile("s_waitcnt vmcnt(0)" ::: "memory");
;         } else {
;             XB_SPIN(xb_ld(&bar[XB_XGEN(x)]) == gen, bar);
;             __builtin_amdgcn_fence(__ATOMIC_ACQUIRE, "agent");
;             asm volatile("s_waitcnt vmcnt(0)" ::: "memory");
;         }
;     }
;     __syncthreads();
.LBB0_357:
	s_waitcnt vmcnt(0)
	v_mov_b32_e32 v0, v209
	s_waitcnt lgkmcnt(0)
	s_barrier
	s_nop 0
	v_cmp_eq_u32_e32 vcc, 0, v0
	s_and_saveexec_b64 s[4:5], vcc
	s_cbranch_execz .LBB0_409
	v_readlane_b32 s12, v255, 8
	v_readlane_b32 s13, v255, 9
	v_mov_b32_e32 v18, 0x20000
	ds_read2_b32 v[20:21], v18 offset1:1
	s_getreg_b32 s14, hwreg(HW_REG_XCC_ID, 0, 4)
	s_and_b32 s14, s14, 15
	s_mul_i32 s32, s56, 11
	s_add_i32 s32, s32, 2
	s_add_i32 s34, s32, 1
	v_mov_b32_e32 v19, 1
	v_mov_b32_e32 v22, 0
	s_waitcnt lgkmcnt(0)
	v_readfirstlane_b32 s24, v20
	v_readfirstlane_b32 s25, v21
	s_lshl_b32 s35, s14, 8
	s_add_u32 s70, s12, s35
	s_addc_u32 s71, s13, 0
	s_add_u32 s72, s70, 0x2400
	s_addc_u32 s73, s71, 0
	s_add_u32 s70, s70, 0x1400
	s_addc_u32 s71, s71, 0
	global_atomic_add v23, v22, v19, s[70:71] sc0
	s_mul_i32 s57, s34, s24
	s_waitcnt vmcnt(0)
	v_readfirstlane_b32 s44, v23
	s_nop 3
	s_add_i32 s44, s44, 1
	s_cmp_lg_u32 s44, s57
	s_cbranch_scc1 .Lfb3_spin
	buffer_wbl2 sc1
	s_waitcnt vmcnt(0)
	s_add_u32 s98, s12, 0x3400
	s_addc_u32 s99, s13, 0
	global_atomic_add v23, v22, v19, s[98:99] sc0
	s_mul_i32 s57, s34, s25
	s_waitcnt vmcnt(0)
	v_readfirstlane_b32 s44, v23
	s_nop 3
	s_add_i32 s44, s44, 1
	s_cmp_lg_u32 s44, s57
	s_cbranch_scc1 .Lfb3_spin
	global_atomic_add v22, v19, s[98:99] offset:256
	s_add_u32 s98, s12, 0x2400
	s_addc_u32 s99, s13, 0
	global_atomic_add v22, v19, s[98:99]
	global_atomic_add v22, v19, s[98:99] offset:256
	global_atomic_add v22, v19, s[98:99] offset:512
	global_atomic_add v22, v19, s[98:99] offset:768
	global_atomic_add v22, v19, s[98:99] offset:1024
	global_atomic_add v22, v19, s[98:99] offset:1280
	global_atomic_add v22, v19, s[98:99] offset:1536
	global_atomic_add v22, v19, s[98:99] offset:1792
	global_atomic_add v22, v19, s[98:99] offset:2048
	global_atomic_add v22, v19, s[98:99] offset:2304
	global_atomic_add v22, v19, s[98:99] offset:2560
	global_atomic_add v22, v19, s[98:99] offset:2816
	global_atomic_add v22, v19, s[98:99] offset:3072
	global_atomic_add v22, v19, s[98:99] offset:3328
	global_atomic_add v22, v19, s[98:99] offset:3584
	global_atomic_add v22, v19, s[98:99] offset:3840

; #define LAS __attribute__((address_space(3)))
; __device__ __forceinline__ KP kargs() { KP k = (KP)__builtin_amdgcn_kernarg_segment_ptr(); asm volatile("" : "+s"(k)); return k; }
; __device__ __forceinline__ int tid_() { int t = threadIdx.x; asm volatile("" : "+v"(t)); return t; }
; __device__ __forceinline__ unsigned xb_ld(unsigned* p)              { return __hip_atomic_load(p, __ATOMIC_RELAXED, __HIP_MEMORY_SCOPE_AGENT); }
; __device__ __forceinline__ unsigned xb_add(unsigned* p, unsigned v) { return __hip_atomic_fetch_add(p, v, __ATOMIC_RELAXED, __HIP_MEMORY_SCOPE_AGENT); }
; __device__ __forceinline__ unsigned xb_xcc_id() { return (unsigned)__builtin_amdgcn_s_getreg((3 << 11) | 20) & 0xFu; }
; __device__ __forceinline__ void grid_barrier(LAS unsigned char* lds) {
;     asm volatile("s_waitcnt vmcnt(0)" ::: "memory");
;     __syncthreads();
;     if (tid_() == 0) {
;         unsigned* bar = (unsigned*)(kargs()->ws + WS_BAR);
;         volatile LAS unsigned* st = (volatile LAS unsigned*)(lds + LDS_BAR_OFF);
;         const unsigned x = xb_xcc_id();
;         __builtin_amdgcn_s_waitcnt(0);
;         unsigned nloc = st[0], nx = st[1];
;         if (nloc == 0u) { xcd_barrier_complete(bar, x, nloc, nx); st[0] = nloc; st[1] = nx; }
;         const unsigned old = xb_add(&bar[XB_XSUB(x)], 1u);
;         const unsigned gen = old / nloc;
;         if (old + 1u == (gen + 1u) * nloc) {
;             __builtin_amdgcn_fence(__ATOMIC_RELEASE, "agent");
;             asm volatile("s_waitcnt vmcnt(0)" ::: "memory");
;             const unsigned og = xb_add(&bar[XB_TOP], 1u);
;             const unsigned tg = og / nx;
;             if (og + 1u == (tg + 1u) * nx) xb_add(&bar[XB_TOPGEN], 1u);
;             else XB_SPIN(xb_ld(&bar[XB_TOPGEN]) == tg, bar);
;             __builtin_amdgcn_fence(__ATOMIC_ACQUIRE, "agent");
;             xb_add(&bar[XB_XGEN(x)], 1u);
;             asm volatile("s_waitcnt vmcnt(0)" ::: "memory");
;         } else {
;             XB_SPIN(xb_ld(&bar[XB_XGEN(x)]) == gen, bar);
;             __builtin_amdgcn_fence(__ATOMIC_ACQUIRE, "agent");
;             asm volatile("s_waitcnt vmcnt(0)" ::: "memory");
;         }
;     }
;     __syncthreads();
.LBB0_426:
	s_or_b64 exec, exec, s[8:9]
	s_waitcnt vmcnt(0)
	v_mov_b32_e32 v0, v209
	s_barrier
	s_nop 0
	v_cmp_eq_u32_e32 vcc, 0, v0
	s_and_saveexec_b64 s[4:5], vcc
	s_cbranch_execz .LBB0_478
	v_readlane_b32 s12, v255, 8
	v_readlane_b32 s13, v255, 9
	v_mov_b32_e32 v18, 0x20000
	ds_read2_b32 v[20:21], v18 offset1:1
	s_getreg_b32 s14, hwreg(HW_REG_XCC_ID, 0, 4)
	s_and_b32 s14, s14, 15
	s_mul_i32 s32, s56, 11
	s_add_i32 s32, s32, 3
	s_add_i32 s34, s32, 1
	v_mov_b32_e32 v19, 1
	v_mov_b32_e32 v22, 0
	s_waitcnt lgkmcnt(0)
	v_readfirstlane_b32 s24, v20
	v_readfirstlane_b32 s25, v21
	s_lshl_b32 s35, s14, 8
	s_add_u32 s70, s12, s35
	s_addc_u32 s71, s13, 0
	s_add_u32 s72, s70, 0x2400
	s_addc_u32 s73, s71, 0
	s_add_u32 s70, s70, 0x1400
	s_addc_u32 s71, s71, 0
	global_atomic_add v23, v22, v19, s[70:71] sc0
	s_mul_i32 s57, s34, s24
	s_waitcnt vmcnt(0)
	v_readfirstlane_b32 s44, v23
	s_nop 3
	s_add_i32 s44, s44, 1
	s_cmp_lg_u32 s44, s57
	s_cbranch_scc1 .Lfb4_spin
	buffer_wbl2 sc1
	s_waitcnt vmcnt(0)
	s_add_u32 s98, s12, 0x3400
	s_addc_u32 s99, s13, 0
	global_atomic_add v23, v22, v19, s[98:99] sc0
	s_mul_i32 s57, s34, s25
	s_waitcnt vmcnt(0)
	v_readfirstlane_b32 s44, v23
	s_nop 3
	s_add_i32 s44, s44, 1
	s_cmp_lg_u32 s44, s57
	s_cbranch_scc1 .Lfb4_spin
	global_atomic_add v22, v19, s[98:99] offset:256
	s_add_u32 s98, s12, 0x2400
	s_addc_u32 s99, s13, 0
	global_atomic_add v22, v19, s[98:99]
	global_atomic_add v22, v19, s[98:99] offset:256
	global_atomic_add v22, v19, s[98:99] offset:512
	global_atomic_add v22, v19, s[98:99] offset:768
	global_atomic_add v22, v19, s[98:99] offset:1024
	global_atomic_add v22, v19, s[98:99] offset:1280
	global_atomic_add v22, v19, s[98:99] offset:1536
	global_atomic_add v22, v19, s[98:99] offset:1792
	global_atomic_add v22, v19, s[98:99] offset:2048
	global_atomic_add v22, v19, s[98:99] offset:2304
	global_atomic_add v22, v19, s[98:99] offset:2560
	global_atomic_add v22, v19, s[98:99] offset:2816
	global_atomic_add v22, v19, s[98:99] offset:3072
	global_atomic_add v22, v19, s[98:99] offset:3328
	global_atomic_add v22, v19, s[98:99] offset:3584
	global_atomic_add v22, v19, s[98:99] offset:3840

; template <class Epi, bool ALIGN_EPI = true, bool SP2 = true>
; __device__ __forceinline__ void gemm_phase(LAS unsigned char* lds, const Gemm g, const Order& S, const Epi& E) {
;     ...
;         const int nt = cur.nkt;
;         for (int t = 0; t < nt; t += 2) {
;             const bool last = (t == nt - 2);
;             const char* a1 = cA + (size_t)(t + 1) * kstep;
;             const char* a2 = last ? nA : cA + (size_t)(t + 2) * kstep; const char* b2 = last ? nB : cB + (size_t)(t + 2) * kstep;
;             const char* a3 = a2 + kstep; const char* b3 = b2 + kstep;
.LBB0_509:
	s_add_i32 s5, s19, -2
	s_add_u32 s15, s68, 0x100
	s_addc_u32 s21, s69, 0
	s_mov_b32 s24, 0
	.p2align	6
	s_nop 0
	s_nop 0
	s_nop 0
	s_nop 0
	s_nop 0
	s_nop 0
	s_nop 0
	s_nop 0
	s_nop 0
	s_nop 0
	s_nop 0

; #define LAS __attribute__((address_space(3)))
; __device__ __forceinline__ KP kargs() { KP k = (KP)__builtin_amdgcn_kernarg_segment_ptr(); asm volatile("" : "+s"(k)); return k; }
; __device__ __forceinline__ int tid_() { int t = threadIdx.x; asm volatile("" : "+v"(t)); return t; }
; __device__ __forceinline__ unsigned xb_ld(unsigned* p)              { return __hip_atomic_load(p, __ATOMIC_RELAXED, __HIP_MEMORY_SCOPE_AGENT); }
; __device__ __forceinline__ unsigned xb_add(unsigned* p, unsigned v) { return __hip_atomic_fetch_add(p, v, __ATOMIC_RELAXED, __HIP_MEMORY_SCOPE_AGENT); }
; __device__ __forceinline__ unsigned xb_xcc_id() { return (unsigned)__builtin_amdgcn_s_getreg((3 << 11) | 20) & 0xFu; }
; __device__ __forceinline__ void grid_barrier(LAS unsigned char* lds) {
;     asm volatile("s_waitcnt vmcnt(0)" ::: "memory");
;     __syncthreads();
;     if (tid_() == 0) {
;         unsigned* bar = (unsigned*)(kargs()->ws + WS_BAR);
;         volatile LAS unsigned* st = (volatile LAS unsigned*)(lds + LDS_BAR_OFF);
;         const unsigned x = xb_xcc_id();
;         __builtin_amdgcn_s_waitcnt(0);
;         unsigned nloc = st[0], nx = st[1];
;         if (nloc == 0u) { xcd_barrier_complete(bar, x, nloc, nx); st[0] = nloc; st[1] = nx; }
;         const unsigned old = xb_add(&bar[XB_XSUB(x)], 1u);
;         const unsigned gen = old / nloc;
;         if (old + 1u == (gen + 1u) * nloc) {
;             __builtin_amdgcn_fence(__ATOMIC_RELEASE, "agent");
;             asm volatile("s_waitcnt vmcnt(0)" ::: "memory");
;             const unsigned og = xb_add(&bar[XB_TOP], 1u);
;             const unsigned tg = og / nx;
;             if (og + 1u == (tg + 1u) * nx) xb_add(&bar[XB_TOPGEN], 1u);
;             else XB_SPIN(xb_ld(&bar[XB_TOPGEN]) == tg, bar);
;             __builtin_amdgcn_fence(__ATOMIC_ACQUIRE, "agent");
;             xb_add(&bar[XB_XGEN(x)], 1u);
;             asm volatile("s_waitcnt vmcnt(0)" ::: "memory");
;         } else {
;             XB_SPIN(xb_ld(&bar[XB_XGEN(x)]) == gen, bar);
;             __builtin_amdgcn_fence(__ATOMIC_ACQUIRE, "agent");
;             asm volatile("s_waitcnt vmcnt(0)" ::: "memory");
;         }
;     }
;     __syncthreads();
.LBB0_587:
	s_waitcnt vmcnt(0)
	v_mov_b32_e32 v0, v209
	s_waitcnt vmcnt(0) lgkmcnt(0)
	s_barrier
	s_nop 0
	v_cmp_eq_u32_e32 vcc, 0, v0
	s_and_saveexec_b64 s[4:5], vcc
	s_mov_b64 s[74:75], 0x48000
	s_cbranch_execz .LBB0_639
	v_readlane_b32 s12, v255, 8
	v_readlane_b32 s13, v255, 9
	v_mov_b32_e32 v18, 0x20000
	ds_read2_b32 v[20:21], v18 offset1:1
	s_getreg_b32 s14, hwreg(HW_REG_XCC_ID, 0, 4)
	s_and_b32 s14, s14, 15
	s_mul_i32 s32, s56, 11
	s_add_i32 s32, s32, 4
	s_add_i32 s34, s32, 1
	v_mov_b32_e32 v19, 1
	v_mov_b32_e32 v22, 0
	s_waitcnt lgkmcnt(0)
	v_readfirstlane_b32 s24, v20
	v_readfirstlane_b32 s25, v21
	s_lshl_b32 s35, s14, 8
	s_add_u32 s70, s12, s35
	s_addc_u32 s71, s13, 0
	s_add_u32 s72, s70, 0x2400
	s_addc_u32 s73, s71, 0
	s_add_u32 s70, s70, 0x1400
	s_addc_u32 s71, s71, 0
	global_atomic_add v23, v22, v19, s[70:71] sc0
	s_mul_i32 s57, s34, s24
	s_waitcnt vmcnt(0)
	v_readfirstlane_b32 s44, v23
	s_nop 3
	s_add_i32 s44, s44, 1
	s_cmp_lg_u32 s44, s57
	s_cbranch_scc1 .Lfb5_spin
	buffer_wbl2 sc1
	s_waitcnt vmcnt(0)
	s_add_u32 s98, s12, 0x3400
	s_addc_u32 s99, s13, 0
	global_atomic_add v23, v22, v19, s[98:99] sc0
	s_mul_i32 s57, s34, s25
	s_waitcnt vmcnt(0)
	v_readfirstlane_b32 s44, v23
	s_nop 3
	s_add_i32 s44, s44, 1
	s_cmp_lg_u32 s44, s57
	s_cbranch_scc1 .Lfb5_spin
	global_atomic_add v22, v19, s[98:99] offset:256
	s_add_u32 s98, s12, 0x2400
	s_addc_u32 s99, s13, 0
	global_atomic_add v22, v19, s[98:99]
	global_atomic_add v22, v19, s[98:99] offset:256
	global_atomic_add v22, v19, s[98:99] offset:512
	global_atomic_add v22, v19, s[98:99] offset:768
	global_atomic_add v22, v19, s[98:99] offset:1024
	global_atomic_add v22, v19, s[98:99] offset:1280
	global_atomic_add v22, v19, s[98:99] offset:1536
	global_atomic_add v22, v19, s[98:99] offset:1792
	global_atomic_add v22, v19, s[98:99] offset:2048
	global_atomic_add v22, v19, s[98:99] offset:2304
	global_atomic_add v22, v19, s[98:99] offset:2560
	global_atomic_add v22, v19, s[98:99] offset:2816
	global_atomic_add v22, v19, s[98:99] offset:3072
	global_atomic_add v22, v19, s[98:99] offset:3328
	global_atomic_add v22, v19, s[98:99] offset:3584
	global_atomic_add v22, v19, s[98:99] offset:3840

; #define LAS __attribute__((address_space(3)))
; __device__ __forceinline__ KP kargs() { KP k = (KP)__builtin_amdgcn_kernarg_segment_ptr(); asm volatile("" : "+s"(k)); return k; }
; __device__ __forceinline__ int tid_() { int t = threadIdx.x; asm volatile("" : "+v"(t)); return t; }
; __device__ __forceinline__ unsigned xb_ld(unsigned* p)              { return __hip_atomic_load(p, __ATOMIC_RELAXED, __HIP_MEMORY_SCOPE_AGENT); }
; __device__ __forceinline__ unsigned xb_add(unsigned* p, unsigned v) { return __hip_atomic_fetch_add(p, v, __ATOMIC_RELAXED, __HIP_MEMORY_SCOPE_AGENT); }
; __device__ __forceinline__ unsigned xb_xcc_id() { return (unsigned)__builtin_amdgcn_s_getreg((3 << 11) | 20) & 0xFu; }
; __device__ __forceinline__ void grid_barrier(LAS unsigned char* lds) {
;     asm volatile("s_waitcnt vmcnt(0)" ::: "memory");
;     __syncthreads();
;     if (tid_() == 0) {
;         unsigned* bar = (unsigned*)(kargs()->ws + WS_BAR);
;         volatile LAS unsigned* st = (volatile LAS unsigned*)(lds + LDS_BAR_OFF);
;         const unsigned x = xb_xcc_id();
;         __builtin_amdgcn_s_waitcnt(0);
;         unsigned nloc = st[0], nx = st[1];
;         if (nloc == 0u) { xcd_barrier_complete(bar, x, nloc, nx); st[0] = nloc; st[1] = nx; }
;         const unsigned old = xb_add(&bar[XB_XSUB(x)], 1u);
;         const unsigned gen = old / nloc;
;         if (old + 1u == (gen + 1u) * nloc) {
;             __builtin_amdgcn_fence(__ATOMIC_RELEASE, "agent");
;             asm volatile("s_waitcnt vmcnt(0)" ::: "memory");
;             const unsigned og = xb_add(&bar[XB_TOP], 1u);
;             const unsigned tg = og / nx;
;             if (og + 1u == (tg + 1u) * nx) xb_add(&bar[XB_TOPGEN], 1u);
;             else XB_SPIN(xb_ld(&bar[XB_TOPGEN]) == tg, bar);
;             __builtin_amdgcn_fence(__ATOMIC_ACQUIRE, "agent");
;             xb_add(&bar[XB_XGEN(x)], 1u);
;             asm volatile("s_waitcnt vmcnt(0)" ::: "memory");
;         } else {
;             XB_SPIN(xb_ld(&bar[XB_XGEN(x)]) == gen, bar);
;             __builtin_amdgcn_fence(__ATOMIC_ACQUIRE, "agent");
;             asm volatile("s_waitcnt vmcnt(0)" ::: "memory");
;         }
;     }
;     __syncthreads();
.LBB0_642:
	s_waitcnt vmcnt(0)
	v_mov_b32_e32 v0, v209
	s_barrier
	s_nop 0
	v_cmp_eq_u32_e32 vcc, 0, v0
	s_and_saveexec_b64 s[4:5], vcc
	s_cbranch_execz .LBB0_694
	v_readlane_b32 s12, v255, 8
	v_readlane_b32 s13, v255, 9
	v_mov_b32_e32 v18, 0x20000
	ds_read2_b32 v[20:21], v18 offset1:1
	s_getreg_b32 s14, hwreg(HW_REG_XCC_ID, 0, 4)
	s_and_b32 s14, s14, 15
	s_mul_i32 s32, s56, 11
	s_add_i32 s32, s32, 5
	s_add_i32 s34, s32, 1
	v_mov_b32_e32 v19, 1
	v_mov_b32_e32 v22, 0
	s_waitcnt lgkmcnt(0)
	v_readfirstlane_b32 s24, v20
	v_readfirstlane_b32 s25, v21
	s_lshl_b32 s35, s14, 8
	s_add_u32 s70, s12, s35
	s_addc_u32 s71, s13, 0
	s_add_u32 s72, s70, 0x2400
	s_addc_u32 s73, s71, 0
	s_add_u32 s70, s70, 0x1400
	s_addc_u32 s71, s71, 0
	global_atomic_add v23, v22, v19, s[70:71] sc0
	s_mul_i32 s57, s34, s24
	s_waitcnt vmcnt(0)
	v_readfirstlane_b32 s44, v23
	s_nop 3
	s_add_i32 s44, s44, 1
	s_cmp_lg_u32 s44, s57
	s_cbranch_scc1 .Lfb6_spin
	buffer_wbl2 sc1
	s_waitcnt vmcnt(0)
	s_add_u32 s98, s12, 0x3400
	s_addc_u32 s99, s13, 0
	global_atomic_add v23, v22, v19, s[98:99] sc0
	s_mul_i32 s57, s34, s25
	s_waitcnt vmcnt(0)
	v_readfirstlane_b32 s44, v23
	s_nop 3
	s_add_i32 s44, s44, 1
	s_cmp_lg_u32 s44, s57
	s_cbranch_scc1 .Lfb6_spin
	global_atomic_add v22, v19, s[98:99] offset:256
	s_add_u32 s98, s12, 0x2400
	s_addc_u32 s99, s13, 0
	global_atomic_add v22, v19, s[98:99]
	global_atomic_add v22, v19, s[98:99] offset:256
	global_atomic_add v22, v19, s[98:99] offset:512
	global_atomic_add v22, v19, s[98:99] offset:768
	global_atomic_add v22, v19, s[98:99] offset:1024
	global_atomic_add v22, v19, s[98:99] offset:1280
	global_atomic_add v22, v19, s[98:99] offset:1536
	global_atomic_add v22, v19, s[98:99] offset:1792
	global_atomic_add v22, v19, s[98:99] offset:2048
	global_atomic_add v22, v19, s[98:99] offset:2304
	global_atomic_add v22, v19, s[98:99] offset:2560
	global_atomic_add v22, v19, s[98:99] offset:2816
	global_atomic_add v22, v19, s[98:99] offset:3072
	global_atomic_add v22, v19, s[98:99] offset:3328
	global_atomic_add v22, v19, s[98:99] offset:3584
	global_atomic_add v22, v19, s[98:99] offset:3840

; template <class Epi, bool ALIGN_EPI = true, bool SP2 = true>
; __device__ __forceinline__ void gemm_phase(LAS unsigned char* lds, const Gemm g, const Order& S, const Epi& E) {
;     ...
;         const int nt = cur.nkt;
;         for (int t = 0; t < nt; t += 2) {
;             const bool last = (t == nt - 2);
;             const char* a1 = cA + (size_t)(t + 1) * kstep;
;             const char* a2 = last ? nA : cA + (size_t)(t + 2) * kstep; const char* b2 = last ? nB : cB + (size_t)(t + 2) * kstep;
;             const char* a3 = a2 + kstep; const char* b3 = b2 + kstep;
;     ...
;         for (int a = 0; a < 2; ++a)
; #pragma unroll
;             for (int b = 0; b < 2; ++b)
; #pragma unroll
;                 for (int m = 0; m < 4; ++m)
; #pragma unroll
;                     for (int n = 0; n < 2; ++n) acc[a][b][m][n] = (f32x4){0.f, 0.f, 0.f, 0.f};
.LBB0_723:
	s_add_i32 s13, s54, -2
	s_add_u32 s15, s68, 0x100
	v_mov_b32_e32 v2, 0
	s_addc_u32 s55, s69, 0
	s_mov_b32 s57, 0
	v_mov_b32_e32 v3, v2
	v_mov_b32_e32 v4, v2
	v_mov_b32_e32 v5, v2
	v_mov_b32_e32 v6, v2
	v_mov_b32_e32 v7, v2
	v_mov_b32_e32 v8, v2
	v_mov_b32_e32 v9, v2
	v_mov_b32_e32 v18, v2
	v_mov_b32_e32 v19, v2
	v_mov_b32_e32 v20, v2
	v_mov_b32_e32 v21, v2
	v_mov_b32_e32 v22, v2
	v_mov_b32_e32 v23, v2
	v_mov_b32_e32 v24, v2
	v_mov_b32_e32 v25, v2
	v_mov_b32_e32 v34, v2
	v_mov_b32_e32 v35, v2
	v_mov_b32_e32 v36, v2
	v_mov_b32_e32 v37, v2
	v_mov_b32_e32 v38, v2
	v_mov_b32_e32 v39, v2
	v_mov_b32_e32 v40, v2
	v_mov_b32_e32 v41, v2
	v_mov_b32_e32 v50, v2
	v_mov_b32_e32 v51, v2
	v_mov_b32_e32 v52, v2
	v_mov_b32_e32 v53, v2
	v_mov_b32_e32 v54, v2
	v_mov_b32_e32 v55, v2
	v_mov_b32_e32 v56, v2
	v_mov_b32_e32 v57, v2
	v_mov_b32_e32 v10, v2
	v_mov_b32_e32 v11, v2
	v_mov_b32_e32 v12, v2
	v_mov_b32_e32 v13, v2
	v_mov_b32_e32 v14, v2
	v_mov_b32_e32 v15, v2
	v_mov_b32_e32 v16, v2
	v_mov_b32_e32 v17, v2
	v_mov_b32_e32 v26, v2
	v_mov_b32_e32 v27, v2
	v_mov_b32_e32 v28, v2
	v_mov_b32_e32 v29, v2
	v_mov_b32_e32 v30, v2
	v_mov_b32_e32 v31, v2
	v_mov_b32_e32 v32, v2
	v_mov_b32_e32 v33, v2
	v_mov_b32_e32 v42, v2
	v_mov_b32_e32 v43, v2
	v_mov_b32_e32 v44, v2
	v_mov_b32_e32 v45, v2
	v_mov_b32_e32 v46, v2
	v_mov_b32_e32 v47, v2
	v_mov_b32_e32 v48, v2
	v_mov_b32_e32 v49, v2
	v_mov_b32_e32 v58, v2
	v_mov_b32_e32 v59, v2
	v_mov_b32_e32 v60, v2
	v_mov_b32_e32 v61, v2
	v_mov_b32_e32 v62, v2
	v_mov_b32_e32 v63, v2
	v_mov_b32_e32 v64, v2
	v_mov_b32_e32 v65, v2
	v_mov_b32_e32 v66, v2
	v_mov_b32_e32 v67, v2
	v_mov_b32_e32 v68, v2
	v_mov_b32_e32 v69, v2
	v_mov_b32_e32 v70, v2
	v_mov_b32_e32 v71, v2
	v_mov_b32_e32 v72, v2
	v_mov_b32_e32 v73, v2
	v_mov_b32_e32 v82, v2
	v_mov_b32_e32 v83, v2
	v_mov_b32_e32 v84, v2
	v_mov_b32_e32 v85, v2
	v_mov_b32_e32 v86, v2
	v_mov_b32_e32 v87, v2
	v_mov_b32_e32 v88, v2
	v_mov_b32_e32 v89, v2
	v_mov_b32_e32 v98, v2
	v_mov_b32_e32 v99, v2
	v_mov_b32_e32 v100, v2
	v_mov_b32_e32 v101, v2
	v_mov_b32_e32 v102, v2
	v_mov_b32_e32 v103, v2
	v_mov_b32_e32 v104, v2
	v_mov_b32_e32 v105, v2
	v_mov_b32_e32 v114, v2
	v_mov_b32_e32 v115, v2
	v_mov_b32_e32 v116, v2
	v_mov_b32_e32 v117, v2
	v_mov_b32_e32 v118, v2
	v_mov_b32_e32 v119, v2
	v_mov_b32_e32 v120, v2
	v_mov_b32_e32 v121, v2
	v_mov_b32_e32 v74, v2
	v_mov_b32_e32 v75, v2
	v_mov_b32_e32 v76, v2
	v_mov_b32_e32 v77, v2
	v_mov_b32_e32 v78, v2
	v_mov_b32_e32 v79, v2
	v_mov_b32_e32 v80, v2
	v_mov_b32_e32 v81, v2
	v_mov_b32_e32 v90, v2
	v_mov_b32_e32 v91, v2
	v_mov_b32_e32 v92, v2
	v_mov_b32_e32 v93, v2
	v_mov_b32_e32 v94, v2
	v_mov_b32_e32 v95, v2
	v_mov_b32_e32 v96, v2
	v_mov_b32_e32 v97, v2
	v_mov_b32_e32 v106, v2
	v_mov_b32_e32 v107, v2
	v_mov_b32_e32 v108, v2
	v_mov_b32_e32 v109, v2
	v_mov_b32_e32 v110, v2
	v_mov_b32_e32 v111, v2
	v_mov_b32_e32 v112, v2
	v_mov_b32_e32 v113, v2
	v_mov_b32_e32 v122, v2
	v_mov_b32_e32 v123, v2
	v_mov_b32_e32 v124, v2
	v_mov_b32_e32 v125, v2
	v_mov_b32_e32 v126, v2
	v_mov_b32_e32 v127, v2
	v_mov_b32_e32 v128, v2
	v_mov_b32_e32 v129, v2
	.p2align	6
	s_nop 0
	s_nop 0
	s_nop 0
	s_nop 0
	s_nop 0
	s_nop 0
	s_nop 0
	s_nop 0
	s_nop 0
	s_nop 0
	s_nop 0

; #define LAS __attribute__((address_space(3)))
; __device__ __forceinline__ KP kargs() { KP k = (KP)__builtin_amdgcn_kernarg_segment_ptr(); asm volatile("" : "+s"(k)); return k; }
; __device__ __forceinline__ int tid_() { int t = threadIdx.x; asm volatile("" : "+v"(t)); return t; }
; __device__ __forceinline__ unsigned xb_ld(unsigned* p)              { return __hip_atomic_load(p, __ATOMIC_RELAXED, __HIP_MEMORY_SCOPE_AGENT); }
; __device__ __forceinline__ unsigned xb_add(unsigned* p, unsigned v) { return __hip_atomic_fetch_add(p, v, __ATOMIC_RELAXED, __HIP_MEMORY_SCOPE_AGENT); }
; __device__ __forceinline__ unsigned xb_xcc_id() { return (unsigned)__builtin_amdgcn_s_getreg((3 << 11) | 20) & 0xFu; }
; __device__ __forceinline__ void grid_barrier(LAS unsigned char* lds) {
;     asm volatile("s_waitcnt vmcnt(0)" ::: "memory");
;     __syncthreads();
;     if (tid_() == 0) {
;         unsigned* bar = (unsigned*)(kargs()->ws + WS_BAR);
;         volatile LAS unsigned* st = (volatile LAS unsigned*)(lds + LDS_BAR_OFF);
;         const unsigned x = xb_xcc_id();
;         __builtin_amdgcn_s_waitcnt(0);
;         unsigned nloc = st[0], nx = st[1];
;         if (nloc == 0u) { xcd_barrier_complete(bar, x, nloc, nx); st[0] = nloc; st[1] = nx; }
;         const unsigned old = xb_add(&bar[XB_XSUB(x)], 1u);
;         const unsigned gen = old / nloc;
;         if (old + 1u == (gen + 1u) * nloc) {
;             __builtin_amdgcn_fence(__ATOMIC_RELEASE, "agent");
;             asm volatile("s_waitcnt vmcnt(0)" ::: "memory");
;             const unsigned og = xb_add(&bar[XB_TOP], 1u);
;             const unsigned tg = og / nx;
;             if (og + 1u == (tg + 1u) * nx) xb_add(&bar[XB_TOPGEN], 1u);
;             else XB_SPIN(xb_ld(&bar[XB_TOPGEN]) == tg, bar);
;             __builtin_amdgcn_fence(__ATOMIC_ACQUIRE, "agent");
;             xb_add(&bar[XB_XGEN(x)], 1u);
;             asm volatile("s_waitcnt vmcnt(0)" ::: "memory");
;         } else {
;             XB_SPIN(xb_ld(&bar[XB_XGEN(x)]) == gen, bar);
;             __builtin_amdgcn_fence(__ATOMIC_ACQUIRE, "agent");
;             asm volatile("s_waitcnt vmcnt(0)" ::: "memory");
;         }
;     }
;     __syncthreads();
.LBB0_738:
	s_waitcnt vmcnt(0)
	v_mov_b32_e32 v0, v209
	s_waitcnt vmcnt(0) lgkmcnt(0)
	s_barrier
	s_nop 0
	v_cmp_eq_u32_e32 vcc, 0, v0
	s_and_saveexec_b64 s[4:5], vcc
	s_cbranch_execz .LBB0_790
	v_readlane_b32 s12, v255, 8
	v_readlane_b32 s13, v255, 9
	v_mov_b32_e32 v18, 0x20000
	ds_read2_b32 v[20:21], v18 offset1:1
	s_getreg_b32 s14, hwreg(HW_REG_XCC_ID, 0, 4)
	s_and_b32 s14, s14, 15
	s_mul_i32 s32, s56, 11
	s_add_i32 s32, s32, 6
	s_add_i32 s34, s32, 1
	v_mov_b32_e32 v19, 1
	v_mov_b32_e32 v22, 0
	s_waitcnt lgkmcnt(0)
	v_readfirstlane_b32 s24, v20
	v_readfirstlane_b32 s25, v21
	s_lshl_b32 s35, s14, 8
	s_add_u32 s70, s12, s35
	s_addc_u32 s71, s13, 0
	s_add_u32 s72, s70, 0x2400
	s_addc_u32 s73, s71, 0
	s_add_u32 s70, s70, 0x1400
	s_addc_u32 s71, s71, 0
	global_atomic_add v23, v22, v19, s[70:71] sc0
	s_mul_i32 s57, s34, s24
	s_waitcnt vmcnt(0)
	v_readfirstlane_b32 s44, v23
	s_nop 3
	s_add_i32 s44, s44, 1
	s_cmp_lg_u32 s44, s57
	s_cbranch_scc1 .Lfb7_spin
	buffer_wbl2 sc1
	s_waitcnt vmcnt(0)
	s_add_u32 s98, s12, 0x3400
	s_addc_u32 s99, s13, 0
	global_atomic_add v23, v22, v19, s[98:99] sc0
	s_mul_i32 s57, s34, s25
	s_waitcnt vmcnt(0)
	v_readfirstlane_b32 s44, v23
	s_nop 3
	s_add_i32 s44, s44, 1
	s_cmp_lg_u32 s44, s57
	s_cbranch_scc1 .Lfb7_spin
	global_atomic_add v22, v19, s[98:99] offset:256
	s_add_u32 s98, s12, 0x2400
	s_addc_u32 s99, s13, 0
	global_atomic_add v22, v19, s[98:99]
	global_atomic_add v22, v19, s[98:99] offset:256
	global_atomic_add v22, v19, s[98:99] offset:512
	global_atomic_add v22, v19, s[98:99] offset:768
	global_atomic_add v22, v19, s[98:99] offset:1024
	global_atomic_add v22, v19, s[98:99] offset:1280
	global_atomic_add v22, v19, s[98:99] offset:1536
	global_atomic_add v22, v19, s[98:99] offset:1792
	global_atomic_add v22, v19, s[98:99] offset:2048
	global_atomic_add v22, v19, s[98:99] offset:2304
	global_atomic_add v22, v19, s[98:99] offset:2560
	global_atomic_add v22, v19, s[98:99] offset:2816
	global_atomic_add v22, v19, s[98:99] offset:3072
	global_atomic_add v22, v19, s[98:99] offset:3328
	global_atomic_add v22, v19, s[98:99] offset:3584
	global_atomic_add v22, v19, s[98:99] offset:3840

; #define LAS __attribute__((address_space(3)))
; __device__ __forceinline__ KP kargs() { KP k = (KP)__builtin_amdgcn_kernarg_segment_ptr(); asm volatile("" : "+s"(k)); return k; }
; __device__ __forceinline__ int tid_() { int t = threadIdx.x; asm volatile("" : "+v"(t)); return t; }
; __device__ __forceinline__ unsigned xb_ld(unsigned* p)              { return __hip_atomic_load(p, __ATOMIC_RELAXED, __HIP_MEMORY_SCOPE_AGENT); }
; __device__ __forceinline__ unsigned xb_add(unsigned* p, unsigned v) { return __hip_atomic_fetch_add(p, v, __ATOMIC_RELAXED, __HIP_MEMORY_SCOPE_AGENT); }
; __device__ __forceinline__ unsigned xb_xcc_id() { return (unsigned)__builtin_amdgcn_s_getreg((3 << 11) | 20) & 0xFu; }
; __device__ __forceinline__ void grid_barrier(LAS unsigned char* lds) {
;     asm volatile("s_waitcnt vmcnt(0)" ::: "memory");
;     __syncthreads();
;     if (tid_() == 0) {
;         unsigned* bar = (unsigned*)(kargs()->ws + WS_BAR);
;         volatile LAS unsigned* st = (volatile LAS unsigned*)(lds + LDS_BAR_OFF);
;         const unsigned x = xb_xcc_id();
;         __builtin_amdgcn_s_waitcnt(0);
;         unsigned nloc = st[0], nx = st[1];
;         if (nloc == 0u) { xcd_barrier_complete(bar, x, nloc, nx); st[0] = nloc; st[1] = nx; }
;         const unsigned old = xb_add(&bar[XB_XSUB(x)], 1u);
;         const unsigned gen = old / nloc;
;         if (old + 1u == (gen + 1u) * nloc) {
;             __builtin_amdgcn_fence(__ATOMIC_RELEASE, "agent");
;             asm volatile("s_waitcnt vmcnt(0)" ::: "memory");
;             const unsigned og = xb_add(&bar[XB_TOP], 1u);
;             const unsigned tg = og / nx;
;             if (og + 1u == (tg + 1u) * nx) xb_add(&bar[XB_TOPGEN], 1u);
;             else XB_SPIN(xb_ld(&bar[XB_TOPGEN]) == tg, bar);
;             __builtin_amdgcn_fence(__ATOMIC_ACQUIRE, "agent");
;             xb_add(&bar[XB_XGEN(x)], 1u);
;             asm volatile("s_waitcnt vmcnt(0)" ::: "memory");
;         } else {
;             XB_SPIN(xb_ld(&bar[XB_XGEN(x)]) == gen, bar);
;             __builtin_amdgcn_fence(__ATOMIC_ACQUIRE, "agent");
;             asm volatile("s_waitcnt vmcnt(0)" ::: "memory");
;         }
;     }
;     __syncthreads();
.LBB0_807:
	s_waitcnt vmcnt(0)
	v_mov_b32_e32 v0, v209
	s_barrier
	s_nop 0
	v_cmp_eq_u32_e32 vcc, 0, v0
	s_and_saveexec_b64 s[4:5], vcc
	s_cbranch_execz .LBB0_859
	v_readlane_b32 s12, v255, 8
	v_readlane_b32 s13, v255, 9
	v_mov_b32_e32 v18, 0x20000
	ds_read2_b32 v[20:21], v18 offset1:1
	s_getreg_b32 s14, hwreg(HW_REG_XCC_ID, 0, 4)
	s_and_b32 s14, s14, 15
	s_mul_i32 s32, s56, 11
	s_add_i32 s32, s32, 7
	s_add_i32 s34, s32, 1
	v_mov_b32_e32 v19, 1
	v_mov_b32_e32 v22, 0
	s_waitcnt lgkmcnt(0)
	v_readfirstlane_b32 s24, v20
	v_readfirstlane_b32 s25, v21
	s_lshl_b32 s35, s14, 8
	s_add_u32 s70, s12, s35
	s_addc_u32 s71, s13, 0
	s_add_u32 s72, s70, 0x2400
	s_addc_u32 s73, s71, 0
	s_add_u32 s70, s70, 0x1400
	s_addc_u32 s71, s71, 0
	global_atomic_add v23, v22, v19, s[70:71] sc0
	s_mul_i32 s57, s34, s24
	s_waitcnt vmcnt(0)
	v_readfirstlane_b32 s44, v23
	s_nop 3
	s_add_i32 s44, s44, 1
	s_cmp_lg_u32 s44, s57
	s_cbranch_scc1 .Lfb8_spin
	buffer_wbl2 sc1
	s_waitcnt vmcnt(0)
	s_add_u32 s98, s12, 0x3400
	s_addc_u32 s99, s13, 0
	global_atomic_add v23, v22, v19, s[98:99] sc0
	s_mul_i32 s57, s34, s25
	s_waitcnt vmcnt(0)
	v_readfirstlane_b32 s44, v23
	s_nop 3
	s_add_i32 s44, s44, 1
	s_cmp_lg_u32 s44, s57
	s_cbranch_scc1 .Lfb8_spin
	global_atomic_add v22, v19, s[98:99] offset:256
	s_add_u32 s98, s12, 0x2400
	s_addc_u32 s99, s13, 0
	global_atomic_add v22, v19, s[98:99]
	global_atomic_add v22, v19, s[98:99] offset:256
	global_atomic_add v22, v19, s[98:99] offset:512
	global_atomic_add v22, v19, s[98:99] offset:768
	global_atomic_add v22, v19, s[98:99] offset:1024
	global_atomic_add v22, v19, s[98:99] offset:1280
	global_atomic_add v22, v19, s[98:99] offset:1536
	global_atomic_add v22, v19, s[98:99] offset:1792
	global_atomic_add v22, v19, s[98:99] offset:2048
	global_atomic_add v22, v19, s[98:99] offset:2304
	global_atomic_add v22, v19, s[98:99] offset:2560
	global_atomic_add v22, v19, s[98:99] offset:2816
	global_atomic_add v22, v19, s[98:99] offset:3072
	global_atomic_add v22, v19, s[98:99] offset:3328
	global_atomic_add v22, v19, s[98:99] offset:3584
	global_atomic_add v22, v19, s[98:99] offset:3840

; template <class Epi, bool ALIGN_EPI = true, bool SP2 = true>
; __device__ __forceinline__ void gemm_phase(LAS unsigned char* lds, const Gemm g, const Order& S, const Epi& E) {
;     ...
;         const char* nA = has_next ? (const char*)(nxt.z ? g.A1 : g.A0) + (size_t)nxt.pm * tstepA + (size_t)nxt.kt0 * kstep : cA; const char* nB = has_next ? (const char*)(nxt.z ? g.B1 : g.B0) + (size_t)nxt.pn * tstepB + (size_t)nxt.kt0 * kstep : cB;
;         const int nt = cur.nkt;
;         for (int t = 0; t < nt; t += 2) {
;             const bool last = (t == nt - 2);
;             const char* a1 = cA + (size_t)(t + 1) * kstep;
;             const char* a2 = last ? nA : cA + (size_t)(t + 2) * kstep; const char* b2 = last ? nB : cB + (size_t)(t + 2) * kstep;
;             const char* a3 = a2 + kstep; const char* b3 = b2 + kstep;
;     ...
;         for (int a = 0; a < 2; ++a)
; #pragma unroll
;             for (int b = 0; b < 2; ++b)
; #pragma unroll
;                 for (int m = 0; m < 4; ++m)
; #pragma unroll
;                     for (int n = 0; n < 2; ++n) acc[a][b][m][n] = (f32x4){0.f, 0.f, 0.f, 0.f};
.LBB0_879:
	s_ashr_i32 s85, s84, 31
	s_lshl_b64 s[54:55], s[84:85], 19
	s_add_u32 s11, s50, s54
	s_addc_u32 s35, s51, s55
	s_and_b64 s[54:55], s[88:89], exec
	s_cselect_b32 s87, s35, s13
	s_cselect_b32 s86, s11, s12
	s_ashr_i32 s83, s82, 31
	s_lshl_b64 s[54:55], s[82:83], 19
	s_add_u32 s11, s52, s54
	s_addc_u32 s35, s53, s55
	s_and_b64 s[54:55], s[88:89], exec
	s_cselect_b32 s89, s35, s93
	s_cselect_b32 s88, s11, s92
	s_add_u32 s12, s12, 0x40080
	s_addc_u32 s13, s13, 0
	s_add_u32 s11, s92, 0x100
	v_mov_b32_e32 v2, 0
	s_addc_u32 s35, s93, 0
	s_mov_b32 s54, -2
	v_mov_b32_e32 v3, v2
	v_mov_b32_e32 v4, v2
	v_mov_b32_e32 v5, v2
	v_mov_b32_e32 v14, v2
	v_mov_b32_e32 v15, v2
	v_mov_b32_e32 v16, v2
	v_mov_b32_e32 v17, v2
	v_mov_b32_e32 v18, v2
	v_mov_b32_e32 v19, v2
	v_mov_b32_e32 v20, v2
	v_mov_b32_e32 v21, v2
	v_mov_b32_e32 v30, v2
	v_mov_b32_e32 v31, v2
	v_mov_b32_e32 v32, v2
	v_mov_b32_e32 v33, v2
	v_mov_b32_e32 v34, v2
	v_mov_b32_e32 v35, v2
	v_mov_b32_e32 v36, v2
	v_mov_b32_e32 v37, v2
	v_mov_b32_e32 v46, v2
	v_mov_b32_e32 v47, v2
	v_mov_b32_e32 v48, v2
	v_mov_b32_e32 v49, v2
	v_mov_b32_e32 v82, v2
	v_mov_b32_e32 v83, v2
	v_mov_b32_e32 v84, v2
	v_mov_b32_e32 v85, v2
	v_mov_b32_e32 v94, v2
	v_mov_b32_e32 v95, v2
	v_mov_b32_e32 v96, v2
	v_mov_b32_e32 v97, v2
	v_mov_b32_e32 v6, v2
	v_mov_b32_e32 v7, v2
	v_mov_b32_e32 v8, v2
	v_mov_b32_e32 v9, v2
	v_mov_b32_e32 v10, v2
	v_mov_b32_e32 v11, v2
	v_mov_b32_e32 v12, v2
	v_mov_b32_e32 v13, v2
	v_mov_b32_e32 v22, v2
	v_mov_b32_e32 v23, v2
	v_mov_b32_e32 v24, v2
	v_mov_b32_e32 v25, v2
	v_mov_b32_e32 v26, v2
	v_mov_b32_e32 v27, v2
	v_mov_b32_e32 v28, v2
	v_mov_b32_e32 v29, v2
	v_mov_b32_e32 v38, v2
	v_mov_b32_e32 v39, v2
	v_mov_b32_e32 v40, v2
	v_mov_b32_e32 v41, v2
	v_mov_b32_e32 v42, v2
	v_mov_b32_e32 v43, v2
	v_mov_b32_e32 v44, v2
	v_mov_b32_e32 v45, v2
	v_mov_b32_e32 v86, v2
	v_mov_b32_e32 v87, v2
	v_mov_b32_e32 v88, v2
	v_mov_b32_e32 v89, v2
	v_mov_b32_e32 v90, v2
	v_mov_b32_e32 v91, v2
	v_mov_b32_e32 v92, v2
	v_mov_b32_e32 v93, v2
	v_mov_b32_e32 v106, v2
	v_mov_b32_e32 v107, v2
	v_mov_b32_e32 v108, v2
	v_mov_b32_e32 v109, v2
	v_mov_b32_e32 v114, v2
	v_mov_b32_e32 v115, v2
	v_mov_b32_e32 v116, v2
	v_mov_b32_e32 v117, v2
	v_mov_b32_e32 v122, v2
	v_mov_b32_e32 v123, v2
	v_mov_b32_e32 v124, v2
	v_mov_b32_e32 v125, v2
	v_mov_b32_e32 v130, v2
	v_mov_b32_e32 v131, v2
	v_mov_b32_e32 v132, v2
	v_mov_b32_e32 v133, v2
	v_mov_b32_e32 v138, v2
	v_mov_b32_e32 v139, v2
	v_mov_b32_e32 v140, v2
	v_mov_b32_e32 v141, v2
	v_mov_b32_e32 v146, v2
	v_mov_b32_e32 v147, v2
	v_mov_b32_e32 v148, v2
	v_mov_b32_e32 v149, v2
	v_mov_b32_e32 v154, v2
	v_mov_b32_e32 v155, v2
	v_mov_b32_e32 v156, v2
	v_mov_b32_e32 v157, v2
	v_mov_b32_e32 v158, v2
	v_mov_b32_e32 v159, v2
	v_mov_b32_e32 v160, v2
	v_mov_b32_e32 v161, v2
	v_mov_b32_e32 v98, v2
	v_mov_b32_e32 v99, v2
	v_mov_b32_e32 v100, v2
	v_mov_b32_e32 v101, v2
	v_mov_b32_e32 v102, v2
	v_mov_b32_e32 v103, v2
	v_mov_b32_e32 v104, v2
	v_mov_b32_e32 v105, v2
	v_mov_b32_e32 v110, v2
	v_mov_b32_e32 v111, v2
	v_mov_b32_e32 v112, v2
	v_mov_b32_e32 v113, v2
	v_mov_b32_e32 v118, v2
	v_mov_b32_e32 v119, v2
	v_mov_b32_e32 v120, v2
	v_mov_b32_e32 v121, v2
	v_mov_b32_e32 v126, v2
	v_mov_b32_e32 v127, v2
	v_mov_b32_e32 v128, v2
	v_mov_b32_e32 v129, v2
	v_mov_b32_e32 v134, v2
	v_mov_b32_e32 v135, v2
	v_mov_b32_e32 v136, v2
	v_mov_b32_e32 v137, v2
	v_mov_b32_e32 v142, v2
	v_mov_b32_e32 v143, v2
	v_mov_b32_e32 v144, v2
	v_mov_b32_e32 v145, v2
	v_mov_b32_e32 v150, v2
	v_mov_b32_e32 v151, v2
	v_mov_b32_e32 v152, v2
	v_mov_b32_e32 v153, v2
	.p2align	6
	s_nop 0
	s_nop 0
	s_nop 0
	s_nop 0
	s_nop 0
	s_nop 0
	s_nop 0
	s_nop 0
	s_nop 0
	s_nop 0
	s_nop 0

; #define LAS __attribute__((address_space(3)))
; __device__ __forceinline__ KP kargs() { KP k = (KP)__builtin_amdgcn_kernarg_segment_ptr(); asm volatile("" : "+s"(k)); return k; }
; __device__ __forceinline__ int tid_() { int t = threadIdx.x; asm volatile("" : "+v"(t)); return t; }
; __device__ __forceinline__ unsigned xb_ld(unsigned* p)              { return __hip_atomic_load(p, __ATOMIC_RELAXED, __HIP_MEMORY_SCOPE_AGENT); }
; __device__ __forceinline__ unsigned xb_add(unsigned* p, unsigned v) { return __hip_atomic_fetch_add(p, v, __ATOMIC_RELAXED, __HIP_MEMORY_SCOPE_AGENT); }
; __device__ __forceinline__ unsigned xb_xcc_id() { return (unsigned)__builtin_amdgcn_s_getreg((3 << 11) | 20) & 0xFu; }
; __device__ __forceinline__ void grid_barrier(LAS unsigned char* lds) {
;     asm volatile("s_waitcnt vmcnt(0)" ::: "memory");
;     __syncthreads();
;     if (tid_() == 0) {
;         unsigned* bar = (unsigned*)(kargs()->ws + WS_BAR);
;         volatile LAS unsigned* st = (volatile LAS unsigned*)(lds + LDS_BAR_OFF);
;         const unsigned x = xb_xcc_id();
;         __builtin_amdgcn_s_waitcnt(0);
;         unsigned nloc = st[0], nx = st[1];
;         if (nloc == 0u) { xcd_barrier_complete(bar, x, nloc, nx); st[0] = nloc; st[1] = nx; }
;         const unsigned old = xb_add(&bar[XB_XSUB(x)], 1u);
;         const unsigned gen = old / nloc;
;         if (old + 1u == (gen + 1u) * nloc) {
;             __builtin_amdgcn_fence(__ATOMIC_RELEASE, "agent");
;             asm volatile("s_waitcnt vmcnt(0)" ::: "memory");
;             const unsigned og = xb_add(&bar[XB_TOP], 1u);
;             const unsigned tg = og / nx;
;             if (og + 1u == (tg + 1u) * nx) xb_add(&bar[XB_TOPGEN], 1u);
;             else XB_SPIN(xb_ld(&bar[XB_TOPGEN]) == tg, bar);
;             __builtin_amdgcn_fence(__ATOMIC_ACQUIRE, "agent");
;             xb_add(&bar[XB_XGEN(x)], 1u);
;             asm volatile("s_waitcnt vmcnt(0)" ::: "memory");
;         } else {
;             XB_SPIN(xb_ld(&bar[XB_XGEN(x)]) == gen, bar);
;             __builtin_amdgcn_fence(__ATOMIC_ACQUIRE, "agent");
;             asm volatile("s_waitcnt vmcnt(0)" ::: "memory");
;         }
;     }
;     __syncthreads();
.LBB0_956:
	s_waitcnt vmcnt(0)
	v_mov_b32_e32 v0, v209
	s_waitcnt lgkmcnt(0)
	s_barrier
	s_nop 0
	v_cmp_eq_u32_e32 vcc, 0, v0
	s_and_saveexec_b64 s[4:5], vcc
	v_readlane_b32 s0, v255, 1
	s_mov_b32 s90, 0x62000
	s_mov_b32 s94, 0x69000
	s_mov_b32 s95, 0x70000
	s_mov_b32 s20, 0x77000
	v_readlane_b32 s1, v255, 2
	s_mov_b32 s96, 0x8c000
	s_mov_b32 s21, 0xfe03f81
	s_cbranch_execz .LBB0_1008
	v_readlane_b32 s12, v255, 8
	v_readlane_b32 s13, v255, 9
	v_mov_b32_e32 v18, 0x20000
	ds_read2_b32 v[20:21], v18 offset1:1
	s_getreg_b32 s14, hwreg(HW_REG_XCC_ID, 0, 4)
	s_and_b32 s14, s14, 15
	s_mul_i32 s32, s86, 11
	s_add_i32 s32, s32, -3
	s_add_i32 s34, s32, 1
	v_mov_b32_e32 v19, 1
	v_mov_b32_e32 v22, 0
	s_waitcnt lgkmcnt(0)
	v_readfirstlane_b32 s24, v20
	v_readfirstlane_b32 s25, v21
	s_lshl_b32 s35, s14, 8
	s_add_u32 s70, s12, s35
	s_addc_u32 s71, s13, 0
	s_add_u32 s72, s70, 0x2400
	s_addc_u32 s73, s71, 0
	s_add_u32 s70, s70, 0x1400
	s_addc_u32 s71, s71, 0
	global_atomic_add v23, v22, v19, s[70:71] sc0
	s_mul_i32 s57, s34, s24
	s_waitcnt vmcnt(0)
	v_readfirstlane_b32 s44, v23
	s_nop 3
	s_add_i32 s44, s44, 1
	s_cmp_lg_u32 s44, s57
	s_cbranch_scc1 .Lfb9_spin
	buffer_wbl2 sc1
	s_waitcnt vmcnt(0)
	s_add_u32 s98, s12, 0x3400
	s_addc_u32 s99, s13, 0
	global_atomic_add v23, v22, v19, s[98:99] sc0
	s_mul_i32 s57, s34, s25
	s_waitcnt vmcnt(0)
	v_readfirstlane_b32 s44, v23
	s_nop 3
	s_add_i32 s44, s44, 1
	s_cmp_lg_u32 s44, s57
	s_cbranch_scc1 .Lfb9_spin
	global_atomic_add v22, v19, s[98:99] offset:256
	s_add_u32 s98, s12, 0x2400
	s_addc_u32 s99, s13, 0
	global_atomic_add v22, v19, s[98:99]
	global_atomic_add v22, v19, s[98:99] offset:256
	global_atomic_add v22, v19, s[98:99] offset:512
	global_atomic_add v22, v19, s[98:99] offset:768
	global_atomic_add v22, v19, s[98:99] offset:1024
	global_atomic_add v22, v19, s[98:99] offset:1280
	global_atomic_add v22, v19, s[98:99] offset:1536
	global_atomic_add v22, v19, s[98:99] offset:1792
	global_atomic_add v22, v19, s[98:99] offset:2048
	global_atomic_add v22, v19, s[98:99] offset:2304
	global_atomic_add v22, v19, s[98:99] offset:2560
	global_atomic_add v22, v19, s[98:99] offset:2816
	global_atomic_add v22, v19, s[98:99] offset:3072
	global_atomic_add v22, v19, s[98:99] offset:3328
	global_atomic_add v22, v19, s[98:99] offset:3584
	global_atomic_add v22, v19, s[98:99] offset:3840

; #define LAS __attribute__((address_space(3)))
; __device__ __forceinline__ KP kargs() { KP k = (KP)__builtin_amdgcn_kernarg_segment_ptr(); asm volatile("" : "+s"(k)); return k; }
; __device__ __forceinline__ int tid_() { int t = threadIdx.x; asm volatile("" : "+v"(t)); return t; }
; __device__ __forceinline__ unsigned xb_ld(unsigned* p)              { return __hip_atomic_load(p, __ATOMIC_RELAXED, __HIP_MEMORY_SCOPE_AGENT); }
; __device__ __forceinline__ unsigned xb_add(unsigned* p, unsigned v) { return __hip_atomic_fetch_add(p, v, __ATOMIC_RELAXED, __HIP_MEMORY_SCOPE_AGENT); }
; __device__ __forceinline__ unsigned xb_xcc_id() { return (unsigned)__builtin_amdgcn_s_getreg((3 << 11) | 20) & 0xFu; }
; __device__ __forceinline__ void grid_barrier(LAS unsigned char* lds) {
;     asm volatile("s_waitcnt vmcnt(0)" ::: "memory");
;     __syncthreads();
;     if (tid_() == 0) {
;         unsigned* bar = (unsigned*)(kargs()->ws + WS_BAR);
;         volatile LAS unsigned* st = (volatile LAS unsigned*)(lds + LDS_BAR_OFF);
;         const unsigned x = xb_xcc_id();
;         __builtin_amdgcn_s_waitcnt(0);
;         unsigned nloc = st[0], nx = st[1];
;         if (nloc == 0u) { xcd_barrier_complete(bar, x, nloc, nx); st[0] = nloc; st[1] = nx; }
;         const unsigned old = xb_add(&bar[XB_XSUB(x)], 1u);
;         const unsigned gen = old / nloc;
;         if (old + 1u == (gen + 1u) * nloc) {
;             __builtin_amdgcn_fence(__ATOMIC_RELEASE, "agent");
;             asm volatile("s_waitcnt vmcnt(0)" ::: "memory");
;             const unsigned og = xb_add(&bar[XB_TOP], 1u);
;             const unsigned tg = og / nx;
;             if (og + 1u == (tg + 1u) * nx) xb_add(&bar[XB_TOPGEN], 1u);
;             else XB_SPIN(xb_ld(&bar[XB_TOPGEN]) == tg, bar);
;             __builtin_amdgcn_fence(__ATOMIC_ACQUIRE, "agent");
;             xb_add(&bar[XB_XGEN(x)], 1u);
;             asm volatile("s_waitcnt vmcnt(0)" ::: "memory");
;         } else {
;             XB_SPIN(xb_ld(&bar[XB_XGEN(x)]) == gen, bar);
;             __builtin_amdgcn_fence(__ATOMIC_ACQUIRE, "agent");
;             asm volatile("s_waitcnt vmcnt(0)" ::: "memory");
;         }
;     }
;     __syncthreads();
.LBB0_1015:
	s_or_b64 exec, exec, s[4:5]
	s_waitcnt vmcnt(0)
	v_mov_b32_e32 v0, v209
	s_barrier
	s_nop 0
	v_cmp_eq_u32_e32 vcc, 0, v0
	s_and_saveexec_b64 s[4:5], vcc
	s_mov_b32 s43, 0x54000
	s_mov_b32 s87, 0x5b000
	s_cbranch_execz .LBB0_1067
	v_readlane_b32 s12, v255, 8
	v_readlane_b32 s13, v255, 9
	v_mov_b32_e32 v18, 0x20000
	ds_read2_b32 v[20:21], v18 offset1:1
	s_getreg_b32 s14, hwreg(HW_REG_XCC_ID, 0, 4)
	s_and_b32 s14, s14, 15
	s_mul_i32 s32, s86, 11
	s_add_i32 s32, s32, -2
	s_add_i32 s34, s32, 1
	v_mov_b32_e32 v19, 1
	v_mov_b32_e32 v22, 0
	s_waitcnt lgkmcnt(0)
	v_readfirstlane_b32 s24, v20
	v_readfirstlane_b32 s25, v21
	s_lshl_b32 s35, s14, 8
	s_add_u32 s70, s12, s35
	s_addc_u32 s71, s13, 0
	s_add_u32 s72, s70, 0x2400
	s_addc_u32 s73, s71, 0
	s_add_u32 s70, s70, 0x1400
	s_addc_u32 s71, s71, 0
	global_atomic_add v23, v22, v19, s[70:71] sc0
	s_mul_i32 s57, s34, s24
	s_waitcnt vmcnt(0)
	v_readfirstlane_b32 s44, v23
	s_nop 3
	s_add_i32 s44, s44, 1
	s_cmp_lg_u32 s44, s57
	s_cbranch_scc1 .Lfb10_spin
	buffer_wbl2 sc1
	s_waitcnt vmcnt(0)
	s_add_u32 s98, s12, 0x3400
	s_addc_u32 s99, s13, 0
	global_atomic_add v23, v22, v19, s[98:99] sc0
	s_mul_i32 s57, s34, s25
	s_waitcnt vmcnt(0)
	v_readfirstlane_b32 s44, v23
	s_nop 3
	s_add_i32 s44, s44, 1
	s_cmp_lg_u32 s44, s57
	s_cbranch_scc1 .Lfb10_spin
	global_atomic_add v22, v19, s[98:99] offset:256
	s_add_u32 s98, s12, 0x2400
	s_addc_u32 s99, s13, 0
	global_atomic_add v22, v19, s[98:99]
	global_atomic_add v22, v19, s[98:99] offset:256
	global_atomic_add v22, v19, s[98:99] offset:512
	global_atomic_add v22, v19, s[98:99] offset:768
	global_atomic_add v22, v19, s[98:99] offset:1024
	global_atomic_add v22, v19, s[98:99] offset:1280
	global_atomic_add v22, v19, s[98:99] offset:1536
	global_atomic_add v22, v19, s[98:99] offset:1792
	global_atomic_add v22, v19, s[98:99] offset:2048
	global_atomic_add v22, v19, s[98:99] offset:2304
	global_atomic_add v22, v19, s[98:99] offset:2560
	global_atomic_add v22, v19, s[98:99] offset:2816
	global_atomic_add v22, v19, s[98:99] offset:3072
	global_atomic_add v22, v19, s[98:99] offset:3328
	global_atomic_add v22, v19, s[98:99] offset:3584
	global_atomic_add v22, v19, s[98:99] offset:3840

; template <class Epi, bool ALIGN_EPI = true, bool SP2 = true>
; __device__ __forceinline__ void gemm_phase(LAS unsigned char* lds, const Gemm g, const Order& S, const Epi& E) {
;     ...
;         const int nt = cur.nkt;
;         for (int t = 0; t < nt; t += 2) {
;             const bool last = (t == nt - 2);
;             const char* a1 = cA + (size_t)(t + 1) * kstep;
;             const char* a2 = last ? nA : cA + (size_t)(t + 2) * kstep; const char* b2 = last ? nB : cB + (size_t)(t + 2) * kstep;
;             const char* a3 = a2 + kstep; const char* b3 = b2 + kstep;
;     ...
;         for (int a = 0; a < 2; ++a)
; #pragma unroll
;             for (int b = 0; b < 2; ++b)
; #pragma unroll
;                 for (int m = 0; m < 4; ++m)
; #pragma unroll
;                     for (int n = 0; n < 2; ++n) acc[a][b][m][n] = (f32x4){0.f, 0.f, 0.f, 0.f};
.LBB0_1096:
	s_add_i32 s13, s55, -2
	s_add_u32 s59, s62, 0x100
	v_mov_b32_e32 v2, 0
	s_addc_u32 s69, s63, 0
	s_mov_b32 s64, 0
	v_mov_b32_e32 v3, v2
	v_mov_b32_e32 v4, v2
	v_mov_b32_e32 v5, v2
	v_mov_b32_e32 v6, v2
	v_mov_b32_e32 v7, v2
	v_mov_b32_e32 v8, v2
	v_mov_b32_e32 v9, v2
	v_mov_b32_e32 v18, v2
	v_mov_b32_e32 v19, v2
	v_mov_b32_e32 v20, v2
	v_mov_b32_e32 v21, v2
	v_mov_b32_e32 v22, v2
	v_mov_b32_e32 v23, v2
	v_mov_b32_e32 v24, v2
	v_mov_b32_e32 v25, v2
	v_mov_b32_e32 v34, v2
	v_mov_b32_e32 v35, v2
	v_mov_b32_e32 v36, v2
	v_mov_b32_e32 v37, v2
	v_mov_b32_e32 v38, v2
	v_mov_b32_e32 v39, v2
	v_mov_b32_e32 v40, v2
	v_mov_b32_e32 v41, v2
	v_mov_b32_e32 v50, v2
	v_mov_b32_e32 v51, v2
	v_mov_b32_e32 v52, v2
	v_mov_b32_e32 v53, v2
	v_mov_b32_e32 v54, v2
	v_mov_b32_e32 v55, v2
	v_mov_b32_e32 v56, v2
	v_mov_b32_e32 v57, v2
	v_mov_b32_e32 v10, v2
	v_mov_b32_e32 v11, v2
	v_mov_b32_e32 v12, v2
	v_mov_b32_e32 v13, v2
	v_mov_b32_e32 v14, v2
	v_mov_b32_e32 v15, v2
	v_mov_b32_e32 v16, v2
	v_mov_b32_e32 v17, v2
	v_mov_b32_e32 v26, v2
	v_mov_b32_e32 v27, v2
	v_mov_b32_e32 v28, v2
	v_mov_b32_e32 v29, v2
	v_mov_b32_e32 v30, v2
	v_mov_b32_e32 v31, v2
	v_mov_b32_e32 v32, v2
	v_mov_b32_e32 v33, v2
	v_mov_b32_e32 v42, v2
	v_mov_b32_e32 v43, v2
	v_mov_b32_e32 v44, v2
	v_mov_b32_e32 v45, v2
	v_mov_b32_e32 v46, v2
	v_mov_b32_e32 v47, v2
	v_mov_b32_e32 v48, v2
	v_mov_b32_e32 v49, v2
	v_mov_b32_e32 v58, v2
	v_mov_b32_e32 v59, v2
	v_mov_b32_e32 v60, v2
	v_mov_b32_e32 v61, v2
	v_mov_b32_e32 v62, v2
	v_mov_b32_e32 v63, v2
	v_mov_b32_e32 v64, v2
	v_mov_b32_e32 v65, v2
	v_mov_b32_e32 v66, v2
	v_mov_b32_e32 v67, v2
	v_mov_b32_e32 v68, v2
	v_mov_b32_e32 v69, v2
	v_mov_b32_e32 v70, v2
	v_mov_b32_e32 v71, v2
	v_mov_b32_e32 v72, v2
	v_mov_b32_e32 v73, v2
	v_mov_b32_e32 v82, v2
	v_mov_b32_e32 v83, v2
	v_mov_b32_e32 v84, v2
	v_mov_b32_e32 v85, v2
	v_mov_b32_e32 v86, v2
	v_mov_b32_e32 v87, v2
	v_mov_b32_e32 v88, v2
	v_mov_b32_e32 v89, v2
	v_mov_b32_e32 v98, v2
	v_mov_b32_e32 v99, v2
	v_mov_b32_e32 v100, v2
	v_mov_b32_e32 v101, v2
	v_mov_b32_e32 v102, v2
	v_mov_b32_e32 v103, v2
	v_mov_b32_e32 v104, v2
	v_mov_b32_e32 v105, v2
	v_mov_b32_e32 v114, v2
	v_mov_b32_e32 v115, v2
	v_mov_b32_e32 v116, v2
	v_mov_b32_e32 v117, v2
	v_mov_b32_e32 v118, v2
	v_mov_b32_e32 v119, v2
	v_mov_b32_e32 v120, v2
	v_mov_b32_e32 v121, v2
	v_mov_b32_e32 v74, v2
	v_mov_b32_e32 v75, v2
	v_mov_b32_e32 v76, v2
	v_mov_b32_e32 v77, v2
	v_mov_b32_e32 v78, v2
	v_mov_b32_e32 v79, v2
	v_mov_b32_e32 v80, v2
	v_mov_b32_e32 v81, v2
	v_mov_b32_e32 v90, v2
	v_mov_b32_e32 v91, v2
	v_mov_b32_e32 v92, v2
	v_mov_b32_e32 v93, v2
	v_mov_b32_e32 v94, v2
	v_mov_b32_e32 v95, v2
	v_mov_b32_e32 v96, v2
	v_mov_b32_e32 v97, v2
	v_mov_b32_e32 v106, v2
	v_mov_b32_e32 v107, v2
	v_mov_b32_e32 v108, v2
	v_mov_b32_e32 v109, v2
	v_mov_b32_e32 v110, v2
	v_mov_b32_e32 v111, v2
	v_mov_b32_e32 v112, v2
	v_mov_b32_e32 v113, v2
	v_mov_b32_e32 v122, v2
	v_mov_b32_e32 v123, v2
	v_mov_b32_e32 v124, v2
	v_mov_b32_e32 v125, v2
	v_mov_b32_e32 v126, v2
	v_mov_b32_e32 v127, v2
	v_mov_b32_e32 v128, v2
	v_mov_b32_e32 v129, v2
	.p2align	6
	s_nop 0
	s_nop 0
	s_nop 0
	s_nop 0
	s_nop 0
	s_nop 0
	s_nop 0
	s_nop 0
	s_nop 0
	s_nop 0
	s_nop 0

; #define LAS __attribute__((address_space(3)))
; __device__ __forceinline__ KP kargs() { KP k = (KP)__builtin_amdgcn_kernarg_segment_ptr(); asm volatile("" : "+s"(k)); return k; }
; __device__ __forceinline__ int tid_() { int t = threadIdx.x; asm volatile("" : "+v"(t)); return t; }
; __device__ __forceinline__ unsigned xb_ld(unsigned* p)              { return __hip_atomic_load(p, __ATOMIC_RELAXED, __HIP_MEMORY_SCOPE_AGENT); }
; __device__ __forceinline__ unsigned xb_add(unsigned* p, unsigned v) { return __hip_atomic_fetch_add(p, v, __ATOMIC_RELAXED, __HIP_MEMORY_SCOPE_AGENT); }
; __device__ __forceinline__ unsigned xb_xcc_id() { return (unsigned)__builtin_amdgcn_s_getreg((3 << 11) | 20) & 0xFu; }
; __device__ __forceinline__ void grid_barrier(LAS unsigned char* lds) {
;     asm volatile("s_waitcnt vmcnt(0)" ::: "memory");
;     __syncthreads();
;     if (tid_() == 0) {
;         unsigned* bar = (unsigned*)(kargs()->ws + WS_BAR);
;         volatile LAS unsigned* st = (volatile LAS unsigned*)(lds + LDS_BAR_OFF);
;         const unsigned x = xb_xcc_id();
;         __builtin_amdgcn_s_waitcnt(0);
;         unsigned nloc = st[0], nx = st[1];
;         if (nloc == 0u) { xcd_barrier_complete(bar, x, nloc, nx); st[0] = nloc; st[1] = nx; }
;         const unsigned old = xb_add(&bar[XB_XSUB(x)], 1u);
;         const unsigned gen = old / nloc;
;         if (old + 1u == (gen + 1u) * nloc) {
;             __builtin_amdgcn_fence(__ATOMIC_RELEASE, "agent");
;             asm volatile("s_waitcnt vmcnt(0)" ::: "memory");
;             const unsigned og = xb_add(&bar[XB_TOP], 1u);
;             const unsigned tg = og / nx;
;             if (og + 1u == (tg + 1u) * nx) xb_add(&bar[XB_TOPGEN], 1u);
;             else XB_SPIN(xb_ld(&bar[XB_TOPGEN]) == tg, bar);
;             __builtin_amdgcn_fence(__ATOMIC_ACQUIRE, "agent");
;             xb_add(&bar[XB_XGEN(x)], 1u);
;             asm volatile("s_waitcnt vmcnt(0)" ::: "memory");
;         } else {
;             XB_SPIN(xb_ld(&bar[XB_XGEN(x)]) == gen, bar);
;             __builtin_amdgcn_fence(__ATOMIC_ACQUIRE, "agent");
;             asm volatile("s_waitcnt vmcnt(0)" ::: "memory");
;         }
;     }
;     __syncthreads();
.LBB0_1111:
	s_waitcnt vmcnt(0)
	v_mov_b32_e32 v0, v209
	s_waitcnt vmcnt(0) lgkmcnt(0)
	s_barrier
	s_nop 0
	v_cmp_eq_u32_e32 vcc, 0, v0
	s_and_saveexec_b64 s[4:5], vcc
	s_cbranch_execz .Lfb11_skip
	v_readlane_b32 s12, v255, 8
	v_readlane_b32 s13, v255, 9
	v_mov_b32_e32 v18, 0x20000
	ds_read2_b32 v[20:21], v18 offset1:1
	s_getreg_b32 s14, hwreg(HW_REG_XCC_ID, 0, 4)
	s_and_b32 s14, s14, 15
	s_mul_i32 s32, s86, 11
	s_add_i32 s32, s32, -1
	s_add_i32 s34, s32, 1
	v_mov_b32_e32 v19, 1
	v_mov_b32_e32 v22, 0
	s_waitcnt lgkmcnt(0)
	v_readfirstlane_b32 s24, v20
	v_readfirstlane_b32 s25, v21
	s_lshl_b32 s35, s14, 8
	s_add_u32 s70, s12, s35
	s_addc_u32 s71, s13, 0
	s_add_u32 s72, s70, 0x2400
	s_addc_u32 s73, s71, 0
	s_add_u32 s70, s70, 0x1400
	s_addc_u32 s71, s71, 0
	global_atomic_add v23, v22, v19, s[70:71] sc0
	s_mul_i32 s57, s34, s24
	s_waitcnt vmcnt(0)
	v_readfirstlane_b32 s44, v23
	s_nop 3
	s_add_i32 s44, s44, 1
	s_cmp_lg_u32 s44, s57
	s_cbranch_scc1 .Lfb11_spin
	buffer_wbl2 sc1
	s_waitcnt vmcnt(0)
	s_add_u32 s98, s12, 0x3400
	s_addc_u32 s99, s13, 0
	global_atomic_add v23, v22, v19, s[98:99] sc0
	s_mul_i32 s57, s34, s25
	s_waitcnt vmcnt(0)
	v_readfirstlane_b32 s44, v23
	s_nop 3
	s_add_i32 s44, s44, 1
	s_cmp_lg_u32 s44, s57
	s_cbranch_scc1 .Lfb11_spin
	global_atomic_add v22, v19, s[98:99] offset:256
	s_add_u32 s98, s12, 0x2400
	s_addc_u32 s99, s13, 0
	global_atomic_add v22, v19, s[98:99]
	global_atomic_add v22, v19, s[98:99] offset:256
	global_atomic_add v22, v19, s[98:99] offset:512
	global_atomic_add v22, v19, s[98:99] offset:768
	global_atomic_add v22, v19, s[98:99] offset:1024
	global_atomic_add v22, v19, s[98:99] offset:1280
	global_atomic_add v22, v19, s[98:99] offset:1536
	global_atomic_add v22, v19, s[98:99] offset:1792
	global_atomic_add v22, v19, s[98:99] offset:2048
	global_atomic_add v22, v19, s[98:99] offset:2304
	global_atomic_add v22, v19, s[98:99] offset:2560
	global_atomic_add v22, v19, s[98:99] offset:2816
	global_atomic_add v22, v19, s[98:99] offset:3072
	global_atomic_add v22, v19, s[98:99] offset:3328
	global_atomic_add v22, v19, s[98:99] offset:3584
	global_atomic_add v22, v19, s[98:99] offset:3840

; __device__ __forceinline__ unsigned xb_ld(unsigned* p)              { return __hip_atomic_load(p, __ATOMIC_RELAXED, __HIP_MEMORY_SCOPE_AGENT); }
; #define XB_SPIN(cond, bar) do { unsigned _sp = 0; while (cond) { __builtin_amdgcn_s_sleep(1); \
;     if ((++_sp & 255u) == 0u) { if (xb_ld(&(bar)[XB_TMO])) break; if (_sp > XB_SPIN_CAP) { atomicAdd(&(bar)[XB_TMO], 1u); break; } } } } while (0)
; __device__ __forceinline__ void grid_barrier(LAS unsigned char* lds) {
;     ...
;             XB_SPIN(xb_ld(&bar[XB_XGEN(x)]) == gen, bar);
;             __builtin_amdgcn_fence(__ATOMIC_ACQUIRE, "agent");
;             asm volatile("s_waitcnt vmcnt(0)" ::: "memory");
;         }
;     }
;     __syncthreads();
.Lfb11_skip:
	s_getpc_b64 s[98:99]
